# epilogue-start wait for the row sums counted (vmcnt(8): only the <=8 younger LDS-DMA prefetches may stay in flight), row-sum loads as global_load
# speedup vs baseline: 1.0073x; 1.0073x over previous
; __device__ __forceinline__ void rsv_load(float (&rsv)[2][4], const GD& g, const pg8::Unit& u, int wr, int fr) {
;     if (g.f2) { const int rg = (u.z / g.nz2) * g.ro1 + u.pm * 256 + wr * 64 + fr;
; #pragma unroll
;         for (int ai = 0; ai < 2; ++ai)
; #pragma unroll
;             for (int m = 0; m < 4; ++m) rsv[ai][m] = g.f2[rg + ai * 128 + m * 16]; }
.LBB0_96:
	s_andn2_b64 vcc, exec, s[2:3]
	s_cbranch_vccnz .LBB0_140
	v_readlane_b32 s24, v254, 52
	s_ashr_i32 s10, s4, 8
	v_readlane_b32 s25, v254, 53
	v_and_b32_e32 v7, 15, v194
	s_cmp_lg_u64 s[24:25], 0
	s_cselect_b64 s[30:31], -1, 0
	s_cmp_eq_u64 s[24:25], 0
	s_waitcnt vmcnt(0)
	v_lshl_or_b32 v144, s10, 6, v7
	v_writelane_b32 v255, s46, 1
	s_cbranch_scc1 .LBB0_99
	s_abs_i32 s2, s79
	v_cvt_f32_u32_e32 v1, s2
	s_sub_i32 s11, 0, s2
	s_xor_b32 s3, s5, s79
	s_abs_i32 s5, s5
	v_rcp_iflag_f32_e32 v1, v1
	s_ashr_i32 s3, s3, 31
	v_mul_f32_e32 v1, 0x4f7ffffe, v1
	v_cvt_u32_f32_e32 v1, v1
	s_nop 0
	v_readfirstlane_b32 s12, v1
	s_mul_i32 s11, s11, s12
	s_mul_hi_u32 s11, s12, s11
	s_add_i32 s12, s12, s11
	s_mul_hi_u32 s11, s5, s12
	s_mul_i32 s12, s11, s2
	s_sub_i32 s5, s5, s12
	s_add_i32 s13, s11, 1
	s_sub_i32 s12, s5, s2
	s_cmp_ge_u32 s5, s2
	s_cselect_b32 s11, s13, s11
	s_cselect_b32 s5, s12, s5
	s_add_i32 s12, s11, 1
	s_cmp_ge_u32 s5, s2
	s_cselect_b32 s2, s12, s11
	s_xor_b32 s2, s2, s3
	s_sub_i32 s2, s2, s3
	s_lshl_b32 s5, s1, 8
	s_mul_i32 s2, s2, s78
	s_add_i32 s2, s2, s5
	v_add_u32_e32 v2, s2, v144
	v_ashrrev_i32_e32 v3, 31, v2
	v_lshl_add_u64 v[2:3], v[2:3], 2, s[24:25]
	global_load_dword v145, v[2:3], off
	global_load_dword v146, v[2:3], off offset:64
	global_load_dword v147, v[2:3], off offset:128
	global_load_dword v148, v[2:3], off offset:192
	global_load_dword v149, v[2:3], off offset:512
	global_load_dword v150, v[2:3], off offset:576
	global_load_dword v151, v[2:3], off offset:640
	global_load_dword v152, v[2:3], off offset:704
	s_branch .LBB0_100

; template <int MODE> __device__ __forceinline__ void gemm_epilogue(f32x4 (&acc)[2][2][4][2], const GD& g, const pg8::Unit& u, int wr, int wc, int fr, int fq, LAS unsigned char* lds, const float (&rsv)[2][4]) {
;     ...
;     if (g.f2) {
; #pragma unroll
;         for (int ai = 0; ai < 2; ++ai)
; #pragma unroll
;             for (int m = 0; m < 4; ++m) { const float rs = rsqrtf(rsv[ai][m] * (1.f / DM) + EPS);
; #pragma unroll
;                 for (int bj = 0; bj < 2; ++bj)
; #pragma unroll
;                     for (int n = 0; n < 2; ++n) acc[ai][bj][m][n] = acc[ai][bj][m][n] * rs; }
;     }
.LBB0_132:
	v_cndmask_b32_e64 v1, 0, 1, s[30:31]
	v_cmp_ne_u32_e64 s[6:7], 1, v1
	s_andn2_b64 vcc, exec, s[30:31]
	s_cbranch_vccnz .LBB0_134
	s_waitcnt vmcnt(8) lgkmcnt(0)
	v_fmamk_f32 v1, v145, 0x3a000000, v203
	v_cmp_gt_f32_e32 vcc, s80, v1
	v_mul_f32_e32 v142, 0x4b800000, v1
	s_nop 0
	v_cndmask_b32_e32 v1, v1, v142, vcc
	v_rsq_f32_e32 v1, v1
	s_nop 0
	v_mul_f32_e32 v142, 0x45800000, v1
	v_cndmask_b32_e32 v142, v1, v142, vcc
	v_fmamk_f32 v1, v146, 0x3a000000, v203
	v_pk_mul_f32 v[128:129], v[142:143], v[128:129] op_sel_hi:[0,1]
	v_pk_mul_f32 v[126:127], v[142:143], v[126:127] op_sel_hi:[0,1]
	v_pk_mul_f32 v[120:121], v[142:143], v[120:121] op_sel_hi:[0,1]
	v_pk_mul_f32 v[118:119], v[142:143], v[118:119] op_sel_hi:[0,1]
	v_pk_mul_f32 v[124:125], v[142:143], v[124:125] op_sel_hi:[0,1]
	v_pk_mul_f32 v[122:123], v[142:143], v[122:123] op_sel_hi:[0,1]
	v_pk_mul_f32 v[116:117], v[142:143], v[116:117] op_sel_hi:[0,1]
	v_pk_mul_f32 v[114:115], v[142:143], v[114:115] op_sel_hi:[0,1]
	v_cmp_gt_f32_e32 vcc, s80, v1
	v_mul_f32_e32 v142, 0x4b800000, v1
	s_nop 0
	v_cndmask_b32_e32 v1, v1, v142, vcc
	v_rsq_f32_e32 v1, v1
	s_nop 0
	v_mul_f32_e32 v142, 0x45800000, v1
	v_cndmask_b32_e32 v142, v1, v142, vcc
	v_fmamk_f32 v1, v147, 0x3a000000, v203
	v_pk_mul_f32 v[112:113], v[142:143], v[112:113] op_sel_hi:[0,1]
	v_pk_mul_f32 v[110:111], v[142:143], v[110:111] op_sel_hi:[0,1]
	v_pk_mul_f32 v[104:105], v[142:143], v[104:105] op_sel_hi:[0,1]
	v_pk_mul_f32 v[102:103], v[142:143], v[102:103] op_sel_hi:[0,1]
	v_pk_mul_f32 v[108:109], v[142:143], v[108:109] op_sel_hi:[0,1]
	v_pk_mul_f32 v[106:107], v[142:143], v[106:107] op_sel_hi:[0,1]
	v_pk_mul_f32 v[100:101], v[142:143], v[100:101] op_sel_hi:[0,1]
	v_pk_mul_f32 v[98:99], v[142:143], v[98:99] op_sel_hi:[0,1]
	v_cmp_gt_f32_e32 vcc, s80, v1
	v_mul_f32_e32 v142, 0x4b800000, v1
	s_nop 0
	v_cndmask_b32_e32 v1, v1, v142, vcc
	v_rsq_f32_e32 v1, v1
	s_nop 0
	v_mul_f32_e32 v142, 0x45800000, v1
	v_cndmask_b32_e32 v142, v1, v142, vcc
	v_fmamk_f32 v1, v148, 0x3a000000, v203
	v_pk_mul_f32 v[96:97], v[142:143], v[96:97] op_sel_hi:[0,1]
	v_pk_mul_f32 v[94:95], v[142:143], v[94:95] op_sel_hi:[0,1]
	v_pk_mul_f32 v[88:89], v[142:143], v[88:89] op_sel_hi:[0,1]
	v_pk_mul_f32 v[86:87], v[142:143], v[86:87] op_sel_hi:[0,1]
	v_pk_mul_f32 v[92:93], v[142:143], v[92:93] op_sel_hi:[0,1]
	v_pk_mul_f32 v[90:91], v[142:143], v[90:91] op_sel_hi:[0,1]
	v_pk_mul_f32 v[84:85], v[142:143], v[84:85] op_sel_hi:[0,1]
	v_pk_mul_f32 v[82:83], v[142:143], v[82:83] op_sel_hi:[0,1]
	v_cmp_gt_f32_e32 vcc, s80, v1
	v_mul_f32_e32 v142, 0x4b800000, v1
	s_nop 0
	v_cndmask_b32_e32 v1, v1, v142, vcc
	v_rsq_f32_e32 v1, v1
	s_nop 0
	v_mul_f32_e32 v142, 0x45800000, v1
	v_cndmask_b32_e32 v142, v1, v142, vcc
	v_fmamk_f32 v1, v149, 0x3a000000, v203
	v_pk_mul_f32 v[80:81], v[142:143], v[80:81] op_sel_hi:[0,1]
	v_pk_mul_f32 v[78:79], v[142:143], v[78:79] op_sel_hi:[0,1]
	v_pk_mul_f32 v[72:73], v[142:143], v[72:73] op_sel_hi:[0,1]
	v_pk_mul_f32 v[70:71], v[142:143], v[70:71] op_sel_hi:[0,1]
	v_pk_mul_f32 v[76:77], v[142:143], v[76:77] op_sel_hi:[0,1]
	v_pk_mul_f32 v[74:75], v[142:143], v[74:75] op_sel_hi:[0,1]
	v_pk_mul_f32 v[68:69], v[142:143], v[68:69] op_sel_hi:[0,1]
	v_pk_mul_f32 v[66:67], v[142:143], v[66:67] op_sel_hi:[0,1]
	v_cmp_gt_f32_e32 vcc, s80, v1
	v_mul_f32_e32 v142, 0x4b800000, v1
	s_nop 0
	v_cndmask_b32_e32 v1, v1, v142, vcc
	v_rsq_f32_e32 v1, v1
	s_nop 0
	v_mul_f32_e32 v142, 0x45800000, v1
	v_cndmask_b32_e32 v142, v1, v142, vcc
	v_fmamk_f32 v1, v150, 0x3a000000, v203
	v_pk_mul_f32 v[64:65], v[142:143], v[64:65] op_sel_hi:[0,1]
	v_pk_mul_f32 v[62:63], v[142:143], v[62:63] op_sel_hi:[0,1]
	v_pk_mul_f32 v[56:57], v[142:143], v[56:57] op_sel_hi:[0,1]
	v_pk_mul_f32 v[54:55], v[142:143], v[54:55] op_sel_hi:[0,1]
	v_pk_mul_f32 v[60:61], v[142:143], v[60:61] op_sel_hi:[0,1]
	v_pk_mul_f32 v[58:59], v[142:143], v[58:59] op_sel_hi:[0,1]
	v_pk_mul_f32 v[52:53], v[142:143], v[52:53] op_sel_hi:[0,1]
	v_pk_mul_f32 v[50:51], v[142:143], v[50:51] op_sel_hi:[0,1]
	v_cmp_gt_f32_e32 vcc, s80, v1
	v_mul_f32_e32 v142, 0x4b800000, v1
	s_nop 0
	v_cndmask_b32_e32 v1, v1, v142, vcc
	v_rsq_f32_e32 v1, v1
	s_nop 0
	v_mul_f32_e32 v142, 0x45800000, v1
	v_cndmask_b32_e32 v142, v1, v142, vcc
	v_fmamk_f32 v1, v151, 0x3a000000, v203
	v_pk_mul_f32 v[48:49], v[142:143], v[48:49] op_sel_hi:[0,1]
	v_pk_mul_f32 v[46:47], v[142:143], v[46:47] op_sel_hi:[0,1]
	v_pk_mul_f32 v[40:41], v[142:143], v[40:41] op_sel_hi:[0,1]
	v_pk_mul_f32 v[38:39], v[142:143], v[38:39] op_sel_hi:[0,1]
	v_pk_mul_f32 v[44:45], v[142:143], v[44:45] op_sel_hi:[0,1]
	v_pk_mul_f32 v[42:43], v[142:143], v[42:43] op_sel_hi:[0,1]
	v_pk_mul_f32 v[36:37], v[142:143], v[36:37] op_sel_hi:[0,1]
	v_pk_mul_f32 v[34:35], v[142:143], v[34:35] op_sel_hi:[0,1]
	v_cmp_gt_f32_e32 vcc, s80, v1
	v_mul_f32_e32 v142, 0x4b800000, v1
	s_nop 0
	v_cndmask_b32_e32 v1, v1, v142, vcc
	v_rsq_f32_e32 v1, v1
	s_nop 0
	v_mul_f32_e32 v142, 0x45800000, v1
	v_cndmask_b32_e32 v142, v1, v142, vcc
	v_fmamk_f32 v1, v152, 0x3a000000, v203
	v_pk_mul_f32 v[32:33], v[142:143], v[32:33] op_sel_hi:[0,1]
	v_pk_mul_f32 v[30:31], v[142:143], v[30:31] op_sel_hi:[0,1]
	v_pk_mul_f32 v[24:25], v[142:143], v[24:25] op_sel_hi:[0,1]
	v_pk_mul_f32 v[22:23], v[142:143], v[22:23] op_sel_hi:[0,1]
	v_pk_mul_f32 v[28:29], v[142:143], v[28:29] op_sel_hi:[0,1]
	v_pk_mul_f32 v[26:27], v[142:143], v[26:27] op_sel_hi:[0,1]
	v_pk_mul_f32 v[20:21], v[142:143], v[20:21] op_sel_hi:[0,1]
	v_pk_mul_f32 v[18:19], v[142:143], v[18:19] op_sel_hi:[0,1]
	v_cmp_gt_f32_e32 vcc, s80, v1
	v_mul_f32_e32 v142, 0x4b800000, v1
	s_nop 0
	v_cndmask_b32_e32 v1, v1, v142, vcc
	v_rsq_f32_e32 v1, v1
	s_nop 0
	v_mul_f32_e32 v142, 0x45800000, v1
	v_cndmask_b32_e32 v142, v1, v142, vcc
	v_pk_mul_f32 v[16:17], v[142:143], v[16:17] op_sel_hi:[0,1]
	v_pk_mul_f32 v[14:15], v[142:143], v[14:15] op_sel_hi:[0,1]
	v_pk_mul_f32 v[8:9], v[142:143], v[8:9] op_sel_hi:[0,1]
	v_pk_mul_f32 v[6:7], v[142:143], v[6:7] op_sel_hi:[0,1]
	v_pk_mul_f32 v[12:13], v[142:143], v[12:13] op_sel_hi:[0,1]
	v_pk_mul_f32 v[10:11], v[142:143], v[10:11] op_sel_hi:[0,1]
	v_pk_mul_f32 v[4:5], v[142:143], v[4:5] op_sel_hi:[0,1]
	v_pk_mul_f32 v[2:3], v[142:143], v[2:3] op_sel_hi:[0,1]
; __device__ __forceinline__ unsigned cvt_pk_bf16(float lo, float hi) { f32x2 v = {lo, hi}; bf16x2_t b = __builtin_convertvector(v, bf16x2_t); return __builtin_bit_cast(unsigned, b); }
; __device__ __forceinline__ float siluf(float v) { return v / (1.f + __expf(-v)); }
; template <int MODE> __device__ __forceinline__ void gemm_epilogue(f32x4 (&acc)[2][2][4][2], const GD& g, const pg8::Unit& u, int wr, int wc, int fr, int fq, LAS unsigned char* lds, const float (&rsv)[2][4]) {
;     ...
;     } else if constexpr (MODE == EP_SWIGLU) {
;         bf16_t* O = (bf16_t*)g.o0; const int col0 = u.pn * 128 + ct;
; #pragma unroll
;         for (int ai = 0; ai < 2; ++ai)
; #pragma unroll
;             for (int m = 0; m < 4; ++m) { const f32x4 g0 = acc[ai][0][m][0], g1 = acc[ai][0][m][1], u0 = acc[ai][1][m][0], u1 = acc[ai][1][m][1]; f32x4 h0, h1;
; #pragma unroll
;                 for (int j = 0; j < 4; ++j) { h0[j] = siluf(g0[j]) * u0[j]; h1[j] = siluf(g1[j]) * u1[j]; }
;                 u32x4 w; w.x = cvt_pk_bf16(h0[0], h0[1]); w.y = cvt_pk_bf16(h0[2], h0[3]); w.z = cvt_pk_bf16(h1[0], h1[1]); w.w = cvt_pk_bf16(h1[2], h1[3]);
;                 *(u32x4*)(O + (size_t)(rt + ai * 128 + m * 16) * DFF + col0) = w; }
.LBB0_134:
	v_lshl_add_u32 v1, s1, 8, v144
	v_lshl_or_b32 v157, s0, 7, v154
	v_readlane_b32 s0, v254, 42
	v_readlane_b32 s1, v254, 43
	v_mul_u32_u24_e32 v1, 0x2c00, v1
	v_mov_b32_e32 v142, 0xbfb8aa3b
	v_mov_b32_e32 v143, 0xbfb8aa3b
	s_mov_b64 s[2:3], -1
	v_lshl_add_u32 v1, v157, 1, v1
	v_pk_mul_f32 v[158:159], v[126:127], v[142:143]
	v_pk_mul_f32 v[160:161], v[128:129], v[142:143]
	v_pk_mul_f32 v[162:163], v[118:119], v[142:143]
	v_pk_mul_f32 v[164:165], v[120:121], v[142:143]
	v_exp_f32_e32 v158, v158
	v_exp_f32_e32 v159, v159
	v_exp_f32_e32 v160, v160
	v_exp_f32_e32 v161, v161
	v_exp_f32_e32 v162, v162
	v_exp_f32_e32 v163, v163
	v_exp_f32_e32 v164, v164
	v_exp_f32_e32 v165, v165
	v_pk_add_f32 v[158:159], v[158:159], 1.0 op_sel_hi:[1,0]
	v_pk_add_f32 v[160:161], v[160:161], 1.0 op_sel_hi:[1,0]
	v_pk_add_f32 v[162:163], v[162:163], 1.0 op_sel_hi:[1,0]
	v_pk_add_f32 v[164:165], v[164:165], 1.0 op_sel_hi:[1,0]
	v_rcp_f32_e32 v158, v158
	v_rcp_f32_e32 v159, v159
	v_rcp_f32_e32 v160, v160
	v_rcp_f32_e32 v161, v161
	v_rcp_f32_e32 v162, v162
	v_rcp_f32_e32 v163, v163
	v_rcp_f32_e32 v164, v164
	v_rcp_f32_e32 v165, v165
	v_pk_mul_f32 v[158:159], v[158:159], v[126:127]
	v_pk_mul_f32 v[160:161], v[160:161], v[128:129]
	v_pk_mul_f32 v[162:163], v[162:163], v[118:119]
	v_pk_mul_f32 v[164:165], v[164:165], v[120:121]
	v_pk_mul_f32 v[158:159], v[158:159], v[122:123]
	v_pk_mul_f32 v[160:161], v[160:161], v[124:125]
	v_pk_mul_f32 v[162:163], v[162:163], v[114:115]
	v_pk_mul_f32 v[164:165], v[164:165], v[116:117]
	v_cvt_pk_bf16_f32 v166, v158, v159
	v_cvt_pk_bf16_f32 v167, v160, v161
	v_cvt_pk_bf16_f32 v168, v162, v163
	v_cvt_pk_bf16_f32 v169, v164, v165
	global_store_dwordx4 v1, v[166:169], s[0:1]
	v_add_u32_e32 v1, 0x2c000, v1
	v_pk_mul_f32 v[158:159], v[110:111], v[142:143]
	v_pk_mul_f32 v[160:161], v[112:113], v[142:143]
	v_pk_mul_f32 v[162:163], v[102:103], v[142:143]
	v_pk_mul_f32 v[164:165], v[104:105], v[142:143]
	v_exp_f32_e32 v158, v158
	v_exp_f32_e32 v159, v159
	v_exp_f32_e32 v160, v160
	v_exp_f32_e32 v161, v161
	v_exp_f32_e32 v162, v162
	v_exp_f32_e32 v163, v163
	v_exp_f32_e32 v164, v164
	v_exp_f32_e32 v165, v165
	v_pk_add_f32 v[158:159], v[158:159], 1.0 op_sel_hi:[1,0]
	v_pk_add_f32 v[160:161], v[160:161], 1.0 op_sel_hi:[1,0]
	v_pk_add_f32 v[162:163], v[162:163], 1.0 op_sel_hi:[1,0]
	v_pk_add_f32 v[164:165], v[164:165], 1.0 op_sel_hi:[1,0]
	v_rcp_f32_e32 v158, v158
	v_rcp_f32_e32 v159, v159
	v_rcp_f32_e32 v160, v160
	v_rcp_f32_e32 v161, v161
	v_rcp_f32_e32 v162, v162
	v_rcp_f32_e32 v163, v163
	v_rcp_f32_e32 v164, v164
	v_rcp_f32_e32 v165, v165
	v_pk_mul_f32 v[158:159], v[158:159], v[110:111]
	v_pk_mul_f32 v[160:161], v[160:161], v[112:113]
	v_pk_mul_f32 v[162:163], v[162:163], v[102:103]
	v_pk_mul_f32 v[164:165], v[164:165], v[104:105]
	v_pk_mul_f32 v[158:159], v[158:159], v[106:107]
	v_pk_mul_f32 v[160:161], v[160:161], v[108:109]
	v_pk_mul_f32 v[162:163], v[162:163], v[98:99]
	v_pk_mul_f32 v[164:165], v[164:165], v[100:101]
	v_cvt_pk_bf16_f32 v166, v158, v159
	v_cvt_pk_bf16_f32 v167, v160, v161
	v_cvt_pk_bf16_f32 v168, v162, v163
	v_cvt_pk_bf16_f32 v169, v164, v165
	global_store_dwordx4 v1, v[166:169], s[0:1]
	v_add_u32_e32 v1, 0x2c000, v1
	v_pk_mul_f32 v[158:159], v[94:95], v[142:143]
	v_pk_mul_f32 v[160:161], v[96:97], v[142:143]
	v_pk_mul_f32 v[162:163], v[86:87], v[142:143]
	v_pk_mul_f32 v[164:165], v[88:89], v[142:143]
	v_exp_f32_e32 v158, v158
	v_exp_f32_e32 v159, v159
	v_exp_f32_e32 v160, v160
	v_exp_f32_e32 v161, v161
	v_exp_f32_e32 v162, v162
	v_exp_f32_e32 v163, v163
	v_exp_f32_e32 v164, v164
	v_exp_f32_e32 v165, v165
	v_pk_add_f32 v[158:159], v[158:159], 1.0 op_sel_hi:[1,0]
	v_pk_add_f32 v[160:161], v[160:161], 1.0 op_sel_hi:[1,0]
	v_pk_add_f32 v[162:163], v[162:163], 1.0 op_sel_hi:[1,0]
	v_pk_add_f32 v[164:165], v[164:165], 1.0 op_sel_hi:[1,0]
	v_rcp_f32_e32 v158, v158
	v_rcp_f32_e32 v159, v159
	v_rcp_f32_e32 v160, v160
	v_rcp_f32_e32 v161, v161
	v_rcp_f32_e32 v162, v162
	v_rcp_f32_e32 v163, v163
	v_rcp_f32_e32 v164, v164
	v_rcp_f32_e32 v165, v165
	v_pk_mul_f32 v[158:159], v[158:159], v[94:95]
	v_pk_mul_f32 v[160:161], v[160:161], v[96:97]
	v_pk_mul_f32 v[162:163], v[162:163], v[86:87]
	v_pk_mul_f32 v[164:165], v[164:165], v[88:89]
	v_pk_mul_f32 v[158:159], v[158:159], v[90:91]
	v_pk_mul_f32 v[160:161], v[160:161], v[92:93]
	v_pk_mul_f32 v[162:163], v[162:163], v[82:83]
	v_pk_mul_f32 v[164:165], v[164:165], v[84:85]
	v_cvt_pk_bf16_f32 v166, v158, v159
	v_cvt_pk_bf16_f32 v167, v160, v161
	v_cvt_pk_bf16_f32 v168, v162, v163
	v_cvt_pk_bf16_f32 v169, v164, v165
	global_store_dwordx4 v1, v[166:169], s[0:1]
	v_add_u32_e32 v1, 0x2c000, v1
	v_pk_mul_f32 v[158:159], v[78:79], v[142:143]
	v_pk_mul_f32 v[160:161], v[80:81], v[142:143]
	v_pk_mul_f32 v[162:163], v[70:71], v[142:143]
	v_pk_mul_f32 v[164:165], v[72:73], v[142:143]
	v_exp_f32_e32 v158, v158
	v_exp_f32_e32 v159, v159
	v_exp_f32_e32 v160, v160
	v_exp_f32_e32 v161, v161
	v_exp_f32_e32 v162, v162
	v_exp_f32_e32 v163, v163
	v_exp_f32_e32 v164, v164
	v_exp_f32_e32 v165, v165
	v_pk_add_f32 v[158:159], v[158:159], 1.0 op_sel_hi:[1,0]
	v_pk_add_f32 v[160:161], v[160:161], 1.0 op_sel_hi:[1,0]
	v_pk_add_f32 v[162:163], v[162:163], 1.0 op_sel_hi:[1,0]
	v_pk_add_f32 v[164:165], v[164:165], 1.0 op_sel_hi:[1,0]
	v_rcp_f32_e32 v158, v158
	v_rcp_f32_e32 v159, v159
	v_rcp_f32_e32 v160, v160
	v_rcp_f32_e32 v161, v161
	v_rcp_f32_e32 v162, v162
	v_rcp_f32_e32 v163, v163
	v_rcp_f32_e32 v164, v164
	v_rcp_f32_e32 v165, v165
	v_pk_mul_f32 v[158:159], v[158:159], v[78:79]
	v_pk_mul_f32 v[160:161], v[160:161], v[80:81]
	v_pk_mul_f32 v[162:163], v[162:163], v[70:71]
	v_pk_mul_f32 v[164:165], v[164:165], v[72:73]
; __device__ __forceinline__ unsigned cvt_pk_bf16(float lo, float hi) { f32x2 v = {lo, hi}; bf16x2_t b = __builtin_convertvector(v, bf16x2_t); return __builtin_bit_cast(unsigned, b); }
; __device__ __forceinline__ float siluf(float v) { return v / (1.f + __expf(-v)); }
; template <int MODE> __device__ __forceinline__ void gemm_epilogue(f32x4 (&acc)[2][2][4][2], const GD& g, const pg8::Unit& u, int wr, int wc, int fr, int fq, LAS unsigned char* lds, const float (&rsv)[2][4]) {
;     ...
;     } else if constexpr (MODE == EP_SWIGLU) {
;         bf16_t* O = (bf16_t*)g.o0; const int col0 = u.pn * 128 + ct;
; #pragma unroll
;         for (int ai = 0; ai < 2; ++ai)
; #pragma unroll
;             for (int m = 0; m < 4; ++m) { const f32x4 g0 = acc[ai][0][m][0], g1 = acc[ai][0][m][1], u0 = acc[ai][1][m][0], u1 = acc[ai][1][m][1]; f32x4 h0, h1;
; #pragma unroll
;                 for (int j = 0; j < 4; ++j) { h0[j] = siluf(g0[j]) * u0[j]; h1[j] = siluf(g1[j]) * u1[j]; }
;                 u32x4 w; w.x = cvt_pk_bf16(h0[0], h0[1]); w.y = cvt_pk_bf16(h0[2], h0[3]); w.z = cvt_pk_bf16(h1[0], h1[1]); w.w = cvt_pk_bf16(h1[2], h1[3]);
;                 *(u32x4*)(O + (size_t)(rt + ai * 128 + m * 16) * DFF + col0) = w; }
	v_pk_mul_f32 v[158:159], v[158:159], v[74:75]
	v_pk_mul_f32 v[160:161], v[160:161], v[76:77]
	v_pk_mul_f32 v[162:163], v[162:163], v[66:67]
	v_pk_mul_f32 v[164:165], v[164:165], v[68:69]
	v_cvt_pk_bf16_f32 v166, v158, v159
	v_cvt_pk_bf16_f32 v167, v160, v161
	v_cvt_pk_bf16_f32 v168, v162, v163
	v_cvt_pk_bf16_f32 v169, v164, v165
	global_store_dwordx4 v1, v[166:169], s[0:1]
	v_add_u32_e32 v1, 0xdc000, v1
	v_pk_mul_f32 v[158:159], v[62:63], v[142:143]
	v_pk_mul_f32 v[160:161], v[64:65], v[142:143]
	v_pk_mul_f32 v[162:163], v[54:55], v[142:143]
	v_pk_mul_f32 v[164:165], v[56:57], v[142:143]
	v_exp_f32_e32 v158, v158
	v_exp_f32_e32 v159, v159
	v_exp_f32_e32 v160, v160
	v_exp_f32_e32 v161, v161
	v_exp_f32_e32 v162, v162
	v_exp_f32_e32 v163, v163
	v_exp_f32_e32 v164, v164
	v_exp_f32_e32 v165, v165
	v_pk_add_f32 v[158:159], v[158:159], 1.0 op_sel_hi:[1,0]
	v_pk_add_f32 v[160:161], v[160:161], 1.0 op_sel_hi:[1,0]
	v_pk_add_f32 v[162:163], v[162:163], 1.0 op_sel_hi:[1,0]
	v_pk_add_f32 v[164:165], v[164:165], 1.0 op_sel_hi:[1,0]
	v_rcp_f32_e32 v158, v158
	v_rcp_f32_e32 v159, v159
	v_rcp_f32_e32 v160, v160
	v_rcp_f32_e32 v161, v161
	v_rcp_f32_e32 v162, v162
	v_rcp_f32_e32 v163, v163
	v_rcp_f32_e32 v164, v164
	v_rcp_f32_e32 v165, v165
	v_pk_mul_f32 v[158:159], v[158:159], v[62:63]
	v_pk_mul_f32 v[160:161], v[160:161], v[64:65]
	v_pk_mul_f32 v[162:163], v[162:163], v[54:55]
	v_pk_mul_f32 v[164:165], v[164:165], v[56:57]
	v_pk_mul_f32 v[158:159], v[158:159], v[58:59]
	v_pk_mul_f32 v[160:161], v[160:161], v[60:61]
	v_pk_mul_f32 v[162:163], v[162:163], v[50:51]
	v_pk_mul_f32 v[164:165], v[164:165], v[52:53]
	v_cvt_pk_bf16_f32 v166, v158, v159
	v_cvt_pk_bf16_f32 v167, v160, v161
	v_cvt_pk_bf16_f32 v168, v162, v163
	v_cvt_pk_bf16_f32 v169, v164, v165
	global_store_dwordx4 v1, v[166:169], s[0:1]
	v_add_u32_e32 v1, 0x2c000, v1
	v_pk_mul_f32 v[158:159], v[46:47], v[142:143]
	v_pk_mul_f32 v[160:161], v[48:49], v[142:143]
	v_pk_mul_f32 v[162:163], v[38:39], v[142:143]
	v_pk_mul_f32 v[164:165], v[40:41], v[142:143]
	v_exp_f32_e32 v158, v158
	v_exp_f32_e32 v159, v159
	v_exp_f32_e32 v160, v160
	v_exp_f32_e32 v161, v161
	v_exp_f32_e32 v162, v162
	v_exp_f32_e32 v163, v163
	v_exp_f32_e32 v164, v164
	v_exp_f32_e32 v165, v165
	v_pk_add_f32 v[158:159], v[158:159], 1.0 op_sel_hi:[1,0]
	v_pk_add_f32 v[160:161], v[160:161], 1.0 op_sel_hi:[1,0]
	v_pk_add_f32 v[162:163], v[162:163], 1.0 op_sel_hi:[1,0]
	v_pk_add_f32 v[164:165], v[164:165], 1.0 op_sel_hi:[1,0]
	v_rcp_f32_e32 v158, v158
	v_rcp_f32_e32 v159, v159
	v_rcp_f32_e32 v160, v160
	v_rcp_f32_e32 v161, v161
	v_rcp_f32_e32 v162, v162
	v_rcp_f32_e32 v163, v163
	v_rcp_f32_e32 v164, v164
	v_rcp_f32_e32 v165, v165
	v_pk_mul_f32 v[158:159], v[158:159], v[46:47]
	v_pk_mul_f32 v[160:161], v[160:161], v[48:49]
	v_pk_mul_f32 v[162:163], v[162:163], v[38:39]
	v_pk_mul_f32 v[164:165], v[164:165], v[40:41]
	v_pk_mul_f32 v[158:159], v[158:159], v[42:43]
	v_pk_mul_f32 v[160:161], v[160:161], v[44:45]
	v_pk_mul_f32 v[162:163], v[162:163], v[34:35]
	v_pk_mul_f32 v[164:165], v[164:165], v[36:37]
	v_cvt_pk_bf16_f32 v166, v158, v159
	v_cvt_pk_bf16_f32 v167, v160, v161
	v_cvt_pk_bf16_f32 v168, v162, v163
	v_cvt_pk_bf16_f32 v169, v164, v165
	global_store_dwordx4 v1, v[166:169], s[0:1]
	v_add_u32_e32 v1, 0x2c000, v1
	v_pk_mul_f32 v[158:159], v[30:31], v[142:143]
	v_pk_mul_f32 v[160:161], v[32:33], v[142:143]
	v_pk_mul_f32 v[162:163], v[22:23], v[142:143]
	v_pk_mul_f32 v[164:165], v[24:25], v[142:143]
	v_exp_f32_e32 v158, v158
	v_exp_f32_e32 v159, v159
	v_exp_f32_e32 v160, v160
	v_exp_f32_e32 v161, v161
	v_exp_f32_e32 v162, v162
	v_exp_f32_e32 v163, v163
	v_exp_f32_e32 v164, v164
	v_exp_f32_e32 v165, v165
	v_pk_add_f32 v[158:159], v[158:159], 1.0 op_sel_hi:[1,0]
	v_pk_add_f32 v[160:161], v[160:161], 1.0 op_sel_hi:[1,0]
	v_pk_add_f32 v[162:163], v[162:163], 1.0 op_sel_hi:[1,0]
	v_pk_add_f32 v[164:165], v[164:165], 1.0 op_sel_hi:[1,0]
	v_rcp_f32_e32 v158, v158
	v_rcp_f32_e32 v159, v159
	v_rcp_f32_e32 v160, v160
	v_rcp_f32_e32 v161, v161
	v_rcp_f32_e32 v162, v162
	v_rcp_f32_e32 v163, v163
	v_rcp_f32_e32 v164, v164
	v_rcp_f32_e32 v165, v165
	v_pk_mul_f32 v[158:159], v[158:159], v[30:31]
	v_pk_mul_f32 v[160:161], v[160:161], v[32:33]
	v_pk_mul_f32 v[162:163], v[162:163], v[22:23]
	v_pk_mul_f32 v[164:165], v[164:165], v[24:25]
	v_pk_mul_f32 v[158:159], v[158:159], v[26:27]
	v_pk_mul_f32 v[160:161], v[160:161], v[28:29]
	v_pk_mul_f32 v[162:163], v[162:163], v[18:19]
	v_pk_mul_f32 v[164:165], v[164:165], v[20:21]
	v_cvt_pk_bf16_f32 v166, v158, v159
	v_cvt_pk_bf16_f32 v167, v160, v161
	v_cvt_pk_bf16_f32 v168, v162, v163
	v_cvt_pk_bf16_f32 v169, v164, v165
	global_store_dwordx4 v1, v[166:169], s[0:1]
	v_add_u32_e32 v1, 0x2c000, v1
	v_pk_mul_f32 v[158:159], v[14:15], v[142:143]
	v_pk_mul_f32 v[160:161], v[16:17], v[142:143]
	v_pk_mul_f32 v[162:163], v[6:7], v[142:143]
	v_pk_mul_f32 v[164:165], v[8:9], v[142:143]
	v_exp_f32_e32 v158, v158
	v_exp_f32_e32 v159, v159
	v_exp_f32_e32 v160, v160
	v_exp_f32_e32 v161, v161
	v_exp_f32_e32 v162, v162
	v_exp_f32_e32 v163, v163
	v_exp_f32_e32 v164, v164
	v_exp_f32_e32 v165, v165
	v_pk_add_f32 v[158:159], v[158:159], 1.0 op_sel_hi:[1,0]
	v_pk_add_f32 v[160:161], v[160:161], 1.0 op_sel_hi:[1,0]
	v_pk_add_f32 v[162:163], v[162:163], 1.0 op_sel_hi:[1,0]
	v_pk_add_f32 v[164:165], v[164:165], 1.0 op_sel_hi:[1,0]
	v_rcp_f32_e32 v158, v158
	v_rcp_f32_e32 v159, v159
	v_rcp_f32_e32 v160, v160
	v_rcp_f32_e32 v161, v161
	v_rcp_f32_e32 v162, v162
	v_rcp_f32_e32 v163, v163
	v_rcp_f32_e32 v164, v164
	v_rcp_f32_e32 v165, v165
	v_pk_mul_f32 v[158:159], v[158:159], v[14:15]
	v_pk_mul_f32 v[160:161], v[160:161], v[16:17]
	v_pk_mul_f32 v[162:163], v[162:163], v[6:7]
	v_pk_mul_f32 v[164:165], v[164:165], v[8:9]
	v_pk_mul_f32 v[158:159], v[158:159], v[10:11]
	v_pk_mul_f32 v[160:161], v[160:161], v[12:13]
	v_pk_mul_f32 v[162:163], v[162:163], v[2:3]
	v_pk_mul_f32 v[164:165], v[164:165], v[4:5]
	v_cvt_pk_bf16_f32 v166, v158, v159
	v_cvt_pk_bf16_f32 v167, v160, v161
	v_cvt_pk_bf16_f32 v168, v162, v163
	v_cvt_pk_bf16_f32 v169, v164, v165
	global_store_dwordx4 v1, v[166:169], s[0:1]
	s_andn2_b64 vcc, exec, s[76:77]
	s_cbranch_vccnz .LBB0_104
; __device__ __forceinline__ void rsv_load(float (&rsv)[2][4], const GD& g, const pg8::Unit& u, int wr, int fr) {
;     if (g.f2) { const int rg = (u.z / g.nz2) * g.ro1 + u.pm * 256 + wr * 64 + fr;
; #pragma unroll
;         for (int ai = 0; ai < 2; ++ai)
; #pragma unroll
;             for (int m = 0; m < 4; ++m) rsv[ai][m] = g.f2[rg + ai * 128 + m * 16]; }
	s_and_b64 vcc, exec, s[6:7]
	s_cbranch_vccnz .LBB0_137
	s_ashr_i32 s0, s26, 31
	v_readlane_b32 s1, v255, 2
	s_xor_b32 s0, s0, s1
	s_abs_i32 s1, s26
	v_readlane_b32 s2, v255, 6
	s_mul_hi_u32 s2, s1, s2
	s_mul_i32 s3, s2, s24
	s_sub_i32 s1, s1, s3
	s_add_i32 s3, s2, 1
	s_sub_i32 s4, s1, s24
	s_cmp_ge_u32 s1, s24
	s_cselect_b32 s2, s3, s2
	s_cselect_b32 s1, s4, s1
	s_add_i32 s3, s2, 1
	s_cmp_ge_u32 s1, s24
	s_cselect_b32 s1, s3, s2
	s_xor_b32 s1, s1, s0
	s_sub_i32 s0, s1, s0
	v_readlane_b32 s1, v254, 59
	s_mul_i32 s0, s0, s1
	s_lshl_b32 s1, s28, 8
	s_add_i32 s0, s0, s1
	v_add_u32_e32 v2, s0, v144
	v_readlane_b32 s0, v254, 52
	v_ashrrev_i32_e32 v3, 31, v2
	v_readlane_b32 s1, v254, 53
	s_nop 1
	v_lshl_add_u64 v[2:3], v[2:3], 2, s[0:1]
	global_load_dword v145, v[2:3], off
	global_load_dword v146, v[2:3], off offset:64
	global_load_dword v147, v[2:3], off offset:128
	global_load_dword v148, v[2:3], off offset:192
	global_load_dword v149, v[2:3], off offset:512
	global_load_dword v150, v[2:3], off offset:576
	global_load_dword v151, v[2:3], off offset:640
	global_load_dword v152, v[2:3], off offset:704

; __device__ __forceinline__ void rsv_load(float (&rsv)[2][4], const GD& g, const pg8::Unit& u, int wr, int fr) {
;     if (g.f2) { const int rg = (u.z / g.nz2) * g.ro1 + u.pm * 256 + wr * 64 + fr;
; #pragma unroll
;         for (int ai = 0; ai < 2; ++ai)
; #pragma unroll
;             for (int m = 0; m < 4; ++m) rsv[ai][m] = g.f2[rg + ai * 128 + m * 16]; }
.LBB0_160:
	s_andn2_b64 vcc, exec, s[2:3]
	s_cbranch_vccnz .LBB0_282
	v_readlane_b32 s12, v254, 52
	s_ashr_i32 s0, s11, 8
	v_readlane_b32 s13, v254, 53
	v_and_b32_e32 v7, 15, v194
	s_cmp_lg_u64 s[12:13], 0
	s_cselect_b64 s[44:45], -1, 0
	s_cmp_eq_u64 s[12:13], 0
	s_waitcnt vmcnt(0)
	v_lshl_or_b32 v154, s0, 6, v7
	v_writelane_b32 v255, s46, 1
	s_cbranch_scc1 .LBB0_163
	s_abs_i32 s1, s79
	v_cvt_f32_u32_e32 v1, s1
	s_sub_i32 s4, 0, s1
	s_abs_i32 s3, s38
	s_xor_b32 s2, s38, s79
	v_rcp_iflag_f32_e32 v1, v1
	s_ashr_i32 s2, s2, 31
	v_mul_f32_e32 v1, 0x4f7ffffe, v1
	v_cvt_u32_f32_e32 v1, v1
	s_nop 0
	v_readfirstlane_b32 s6, v1
	s_mul_i32 s4, s4, s6
	s_mul_hi_u32 s4, s6, s4
	s_add_i32 s6, s6, s4
	s_mul_hi_u32 s4, s3, s6
	s_mul_i32 s6, s4, s1
	s_sub_i32 s3, s3, s6
	s_add_i32 s7, s4, 1
	s_sub_i32 s6, s3, s1
	s_cmp_ge_u32 s3, s1
	s_cselect_b32 s4, s7, s4
	s_cselect_b32 s3, s6, s3
	s_add_i32 s6, s4, 1
	s_cmp_ge_u32 s3, s1
	s_cselect_b32 s1, s6, s4
	s_xor_b32 s1, s1, s2
	s_sub_i32 s1, s1, s2
	s_lshl_b32 s3, s56, 8
	s_mul_i32 s1, s1, s78
	s_add_i32 s1, s1, s3
	v_add_u32_e32 v2, s1, v154
	v_ashrrev_i32_e32 v3, 31, v2
	v_lshl_add_u64 v[2:3], v[2:3], 2, s[12:13]
	global_load_dword v155, v[2:3], off
	global_load_dword v156, v[2:3], off offset:64
	global_load_dword v157, v[2:3], off offset:128
	global_load_dword v158, v[2:3], off offset:192
	global_load_dword v159, v[2:3], off offset:512
	global_load_dword v160, v[2:3], off offset:576
	global_load_dword v161, v[2:3], off offset:640
	global_load_dword v162, v[2:3], off offset:704
	s_branch .LBB0_164

; __device__ __forceinline__ void rsv_load(float (&rsv)[2][4], const GD& g, const pg8::Unit& u, int wr, int fr) {
;     if (g.f2) { const int rg = (u.z / g.nz2) * g.ro1 + u.pm * 256 + wr * 64 + fr;
; #pragma unroll
;         for (int ai = 0; ai < 2; ++ai)
; #pragma unroll
;             for (int m = 0; m < 4; ++m) rsv[ai][m] = g.f2[rg + ai * 128 + m * 16]; }
.Lres_done:
	s_andn2_b64 vcc, exec, s[92:93]
	s_mov_b64 s[2:3], -1
	s_cbranch_vccnz .LBB0_168
	s_and_b64 vcc, exec, s[44:45]
	s_cbranch_vccz .LBB0_167
	s_abs_i32 s3, s14
	s_mul_hi_u32 s8, s3, s0
	s_mul_i32 s9, s8, s1
	s_ashr_i32 s2, s14, 31
	s_sub_i32 s3, s3, s9
	s_xor_b32 s2, s2, s52
	s_add_i32 s9, s8, 1
	s_sub_i32 s12, s3, s1
	s_cmp_ge_u32 s3, s1
	s_cselect_b32 s8, s9, s8
	s_cselect_b32 s3, s12, s3
	s_add_i32 s9, s8, 1
	s_cmp_ge_u32 s3, s1
	s_cselect_b32 s3, s9, s8
	s_xor_b32 s3, s3, s2
	s_sub_i32 s2, s3, s2
	v_readlane_b32 s3, v254, 59
	s_mul_i32 s2, s2, s3
	s_lshl_b32 s3, s15, 8
	s_add_i32 s2, s2, s3
	s_waitcnt lgkmcnt(0)
	v_add_u32_e32 v2, s2, v154
	v_readlane_b32 s2, v254, 52
	v_ashrrev_i32_e32 v3, 31, v2
	v_readlane_b32 s3, v254, 53
	s_nop 1
	v_lshl_add_u64 v[2:3], v[2:3], 2, s[2:3]
	global_load_dword v155, v[2:3], off
	global_load_dword v156, v[2:3], off offset:64
	global_load_dword v157, v[2:3], off offset:128
	global_load_dword v158, v[2:3], off offset:192
	global_load_dword v159, v[2:3], off offset:512
	global_load_dword v160, v[2:3], off offset:576
	global_load_dword v161, v[2:3], off offset:640
	global_load_dword v162, v[2:3], off offset:704
	s_branch .LBB0_167

; __device__ __forceinline__ void rsv_load(float (&rsv)[2][4], const GD& g, const pg8::Unit& u, int wr, int fr) {
;     if (g.f2) { const int rg = (u.z / g.nz2) * g.ro1 + u.pm * 256 + wr * 64 + fr;
; #pragma unroll
;         for (int ai = 0; ai < 2; ++ai)
; #pragma unroll
;             for (int m = 0; m < 4; ++m) rsv[ai][m] = g.f2[rg + ai * 128 + m * 16]; }
.LBB0_301:
	s_andn2_b64 vcc, exec, s[2:3]
	s_cbranch_vccnz .LBB0_351
	s_ashr_i32 s5, s1, 8
	v_readlane_b32 s14, v254, 52
	s_lshl_b32 s17, s5, 6
	v_readlane_b32 s15, v254, 53
	s_waitcnt vmcnt(0) lgkmcnt(0)
	v_and_b32_e32 v162, 15, v194
	s_cmp_lg_u64 s[14:15], 0
	s_cselect_b64 s[44:45], -1, 0
	s_cmp_eq_u64 s[14:15], 0
	v_or_b32_e32 v163, s17, v162
	s_mov_b32 s13, s59
	v_writelane_b32 v255, s46, 1
	s_cbranch_scc1 .LBB0_304
	s_abs_i32 s2, s79
	v_cvt_f32_u32_e32 v1, s2
	s_sub_i32 s10, 0, s2
	s_xor_b32 s3, s4, s79
	s_abs_i32 s4, s4
	v_rcp_iflag_f32_e32 v1, v1
	s_ashr_i32 s3, s3, 31
	v_mul_f32_e32 v1, 0x4f7ffffe, v1
	v_cvt_u32_f32_e32 v1, v1
	s_nop 0
	v_readfirstlane_b32 s11, v1
	s_mul_i32 s10, s10, s11
	s_mul_hi_u32 s10, s11, s10
	s_add_i32 s11, s11, s10
	s_mul_hi_u32 s10, s4, s11
	s_mul_i32 s11, s10, s2
	s_sub_i32 s4, s4, s11
	s_add_i32 s12, s10, 1
	s_sub_i32 s11, s4, s2
	s_cmp_ge_u32 s4, s2
	s_cselect_b32 s10, s12, s10
	s_cselect_b32 s4, s11, s4
	s_add_i32 s11, s10, 1
	s_cmp_ge_u32 s4, s2
	s_cselect_b32 s2, s11, s10
	s_xor_b32 s2, s2, s3
	s_sub_i32 s2, s2, s3
	s_lshl_b32 s4, s0, 8
	s_mul_i32 s2, s2, s78
	s_add_i32 s2, s2, s4
	v_add_u32_e32 v2, s2, v163
	v_ashrrev_i32_e32 v3, 31, v2
	v_lshl_add_u64 v[2:3], v[2:3], 2, s[14:15]
	global_load_dword v164, v[2:3], off
	global_load_dword v165, v[2:3], off offset:64
	global_load_dword v166, v[2:3], off offset:128
	global_load_dword v167, v[2:3], off offset:192
	global_load_dword v168, v[2:3], off offset:512
	global_load_dword v169, v[2:3], off offset:576
	global_load_dword v170, v[2:3], off offset:640
	global_load_dword v171, v[2:3], off offset:704
	s_branch .LBB0_305

; template <int MODE> __device__ __forceinline__ void gemm_epilogue(f32x4 (&acc)[2][2][4][2], const GD& g, const pg8::Unit& u, int wr, int wc, int fr, int fq, LAS unsigned char* lds, const float (&rsv)[2][4]) {
;     ...
;     if (g.f2) {
; #pragma unroll
;         for (int ai = 0; ai < 2; ++ai)
; #pragma unroll
;             for (int m = 0; m < 4; ++m) { const float rs = rsqrtf(rsv[ai][m] * (1.f / DM) + EPS);
; #pragma unroll
;                 for (int bj = 0; bj < 2; ++bj)
; #pragma unroll
;                     for (int n = 0; n < 2; ++n) acc[ai][bj][m][n] = acc[ai][bj][m][n] * rs; }
;     }
.LBB0_337:
	v_cndmask_b32_e64 v1, 0, 1, s[44:45]
	v_cmp_ne_u32_e64 s[6:7], 1, v1
	s_andn2_b64 vcc, exec, s[44:45]
	s_cbranch_vccnz .LBB0_339
	s_waitcnt vmcnt(8) lgkmcnt(0)
	v_fmamk_f32 v1, v164, 0x3a000000, v203
	v_cmp_gt_f32_e32 vcc, s80, v1
	v_mul_f32_e32 v146, 0x4b800000, v1
	s_nop 0
	v_cndmask_b32_e32 v1, v1, v146, vcc
	v_rsq_f32_e32 v1, v1
	s_nop 0
	v_mul_f32_e32 v146, 0x45800000, v1
	v_cndmask_b32_e32 v146, v1, v146, vcc
	v_fmamk_f32 v1, v165, 0x3a000000, v203
	v_pk_mul_f32 v[128:129], v[146:147], v[128:129] op_sel_hi:[0,1]
	v_pk_mul_f32 v[126:127], v[146:147], v[126:127] op_sel_hi:[0,1]
	v_pk_mul_f32 v[124:125], v[146:147], v[124:125] op_sel_hi:[0,1]
	v_pk_mul_f32 v[122:123], v[146:147], v[122:123] op_sel_hi:[0,1]
	v_pk_mul_f32 v[116:117], v[146:147], v[116:117] op_sel_hi:[0,1]
	v_pk_mul_f32 v[114:115], v[146:147], v[114:115] op_sel_hi:[0,1]
	v_pk_mul_f32 v[108:109], v[146:147], v[108:109] op_sel_hi:[0,1]
	v_pk_mul_f32 v[106:107], v[146:147], v[106:107] op_sel_hi:[0,1]
	v_cmp_gt_f32_e32 vcc, s80, v1
	v_mul_f32_e32 v146, 0x4b800000, v1
	s_nop 0
	v_cndmask_b32_e32 v1, v1, v146, vcc
	v_rsq_f32_e32 v1, v1
	s_nop 0
	v_mul_f32_e32 v146, 0x45800000, v1
	v_cndmask_b32_e32 v146, v1, v146, vcc
	v_fmamk_f32 v1, v166, 0x3a000000, v203
	v_pk_mul_f32 v[120:121], v[146:147], v[120:121] op_sel_hi:[0,1]
	v_pk_mul_f32 v[118:119], v[146:147], v[118:119] op_sel_hi:[0,1]
	v_pk_mul_f32 v[112:113], v[146:147], v[112:113] op_sel_hi:[0,1]
	v_pk_mul_f32 v[110:111], v[146:147], v[110:111] op_sel_hi:[0,1]
	v_pk_mul_f32 v[100:101], v[146:147], v[100:101] op_sel_hi:[0,1]
	v_pk_mul_f32 v[98:99], v[146:147], v[98:99] op_sel_hi:[0,1]
	v_pk_mul_f32 v[92:93], v[146:147], v[92:93] op_sel_hi:[0,1]
	v_pk_mul_f32 v[90:91], v[146:147], v[90:91] op_sel_hi:[0,1]
	v_cmp_gt_f32_e32 vcc, s80, v1
	v_mul_f32_e32 v146, 0x4b800000, v1
	s_nop 0
	v_cndmask_b32_e32 v1, v1, v146, vcc
	v_rsq_f32_e32 v1, v1
	s_nop 0
	v_mul_f32_e32 v146, 0x45800000, v1
	v_cndmask_b32_e32 v146, v1, v146, vcc
	v_fmamk_f32 v1, v167, 0x3a000000, v203
	v_pk_mul_f32 v[104:105], v[146:147], v[104:105] op_sel_hi:[0,1]
	v_pk_mul_f32 v[102:103], v[146:147], v[102:103] op_sel_hi:[0,1]
	v_pk_mul_f32 v[96:97], v[146:147], v[96:97] op_sel_hi:[0,1]
	v_pk_mul_f32 v[94:95], v[146:147], v[94:95] op_sel_hi:[0,1]
	v_pk_mul_f32 v[84:85], v[146:147], v[84:85] op_sel_hi:[0,1]
	v_pk_mul_f32 v[82:83], v[146:147], v[82:83] op_sel_hi:[0,1]
	v_pk_mul_f32 v[76:77], v[146:147], v[76:77] op_sel_hi:[0,1]
	v_pk_mul_f32 v[74:75], v[146:147], v[74:75] op_sel_hi:[0,1]
	v_cmp_gt_f32_e32 vcc, s80, v1
	v_mul_f32_e32 v146, 0x4b800000, v1
	s_nop 0
	v_cndmask_b32_e32 v1, v1, v146, vcc
	v_rsq_f32_e32 v1, v1
	s_nop 0
	v_mul_f32_e32 v146, 0x45800000, v1
	v_cndmask_b32_e32 v146, v1, v146, vcc
	v_fmamk_f32 v1, v168, 0x3a000000, v203
	v_pk_mul_f32 v[88:89], v[146:147], v[88:89] op_sel_hi:[0,1]
	v_pk_mul_f32 v[86:87], v[146:147], v[86:87] op_sel_hi:[0,1]
	v_pk_mul_f32 v[80:81], v[146:147], v[80:81] op_sel_hi:[0,1]
	v_pk_mul_f32 v[78:79], v[146:147], v[78:79] op_sel_hi:[0,1]
	v_pk_mul_f32 v[72:73], v[146:147], v[72:73] op_sel_hi:[0,1]
	v_pk_mul_f32 v[70:71], v[146:147], v[70:71] op_sel_hi:[0,1]
	v_pk_mul_f32 v[68:69], v[146:147], v[68:69] op_sel_hi:[0,1]
	v_pk_mul_f32 v[66:67], v[146:147], v[66:67] op_sel_hi:[0,1]
	v_cmp_gt_f32_e32 vcc, s80, v1
	v_mul_f32_e32 v146, 0x4b800000, v1
	s_nop 0
	v_cndmask_b32_e32 v1, v1, v146, vcc
	v_rsq_f32_e32 v1, v1
	s_nop 0
	v_mul_f32_e32 v146, 0x45800000, v1
	v_cndmask_b32_e32 v146, v1, v146, vcc
	v_fmamk_f32 v1, v169, 0x3a000000, v203
	v_pk_mul_f32 v[64:65], v[146:147], v[64:65] op_sel_hi:[0,1]
	v_pk_mul_f32 v[62:63], v[146:147], v[62:63] op_sel_hi:[0,1]
	v_pk_mul_f32 v[60:61], v[146:147], v[60:61] op_sel_hi:[0,1]
	v_pk_mul_f32 v[58:59], v[146:147], v[58:59] op_sel_hi:[0,1]
	v_pk_mul_f32 v[52:53], v[146:147], v[52:53] op_sel_hi:[0,1]
	v_pk_mul_f32 v[50:51], v[146:147], v[50:51] op_sel_hi:[0,1]
	v_pk_mul_f32 v[44:45], v[146:147], v[44:45] op_sel_hi:[0,1]
	v_pk_mul_f32 v[42:43], v[146:147], v[42:43] op_sel_hi:[0,1]
	v_cmp_gt_f32_e32 vcc, s80, v1
	v_mul_f32_e32 v146, 0x4b800000, v1
	s_nop 0
	v_cndmask_b32_e32 v1, v1, v146, vcc
	v_rsq_f32_e32 v1, v1
	s_nop 0
	v_mul_f32_e32 v146, 0x45800000, v1
	v_cndmask_b32_e32 v146, v1, v146, vcc
	v_fmamk_f32 v1, v170, 0x3a000000, v203
	v_pk_mul_f32 v[56:57], v[146:147], v[56:57] op_sel_hi:[0,1]
	v_pk_mul_f32 v[54:55], v[146:147], v[54:55] op_sel_hi:[0,1]
	v_pk_mul_f32 v[48:49], v[146:147], v[48:49] op_sel_hi:[0,1]
	v_pk_mul_f32 v[46:47], v[146:147], v[46:47] op_sel_hi:[0,1]
	v_pk_mul_f32 v[36:37], v[146:147], v[36:37] op_sel_hi:[0,1]
	v_pk_mul_f32 v[34:35], v[146:147], v[34:35] op_sel_hi:[0,1]
	v_pk_mul_f32 v[28:29], v[146:147], v[28:29] op_sel_hi:[0,1]
	v_pk_mul_f32 v[26:27], v[146:147], v[26:27] op_sel_hi:[0,1]
	v_cmp_gt_f32_e32 vcc, s80, v1
	v_mul_f32_e32 v146, 0x4b800000, v1
	s_nop 0
	v_cndmask_b32_e32 v1, v1, v146, vcc
	v_rsq_f32_e32 v1, v1
	s_nop 0
	v_mul_f32_e32 v146, 0x45800000, v1
	v_cndmask_b32_e32 v146, v1, v146, vcc
	v_fmamk_f32 v1, v171, 0x3a000000, v203
	v_pk_mul_f32 v[40:41], v[146:147], v[40:41] op_sel_hi:[0,1]
	v_pk_mul_f32 v[38:39], v[146:147], v[38:39] op_sel_hi:[0,1]
	v_pk_mul_f32 v[32:33], v[146:147], v[32:33] op_sel_hi:[0,1]
	v_pk_mul_f32 v[30:31], v[146:147], v[30:31] op_sel_hi:[0,1]
	v_pk_mul_f32 v[20:21], v[146:147], v[20:21] op_sel_hi:[0,1]
	v_pk_mul_f32 v[18:19], v[146:147], v[18:19] op_sel_hi:[0,1]
	v_pk_mul_f32 v[12:13], v[146:147], v[12:13] op_sel_hi:[0,1]
	v_pk_mul_f32 v[10:11], v[146:147], v[10:11] op_sel_hi:[0,1]
	v_cmp_gt_f32_e32 vcc, s80, v1
	v_mul_f32_e32 v146, 0x4b800000, v1
	s_nop 0
	v_cndmask_b32_e32 v1, v1, v146, vcc
	v_rsq_f32_e32 v1, v1
	s_nop 0
	v_mul_f32_e32 v146, 0x45800000, v1
	v_cndmask_b32_e32 v146, v1, v146, vcc
	v_pk_mul_f32 v[24:25], v[146:147], v[24:25] op_sel_hi:[0,1]
	v_pk_mul_f32 v[22:23], v[146:147], v[22:23] op_sel_hi:[0,1]
	v_pk_mul_f32 v[16:17], v[146:147], v[16:17] op_sel_hi:[0,1]
	v_pk_mul_f32 v[14:15], v[146:147], v[14:15] op_sel_hi:[0,1]
	v_pk_mul_f32 v[8:9], v[146:147], v[8:9] op_sel_hi:[0,1]
	v_pk_mul_f32 v[6:7], v[146:147], v[6:7] op_sel_hi:[0,1]
	v_pk_mul_f32 v[4:5], v[146:147], v[4:5] op_sel_hi:[0,1]
	v_pk_mul_f32 v[2:3], v[146:147], v[2:3] op_sel_hi:[0,1]

; __device__ __forceinline__ void rsv_load(float (&rsv)[2][4], const GD& g, const pg8::Unit& u, int wr, int fr) {
;     if (g.f2) { const int rg = (u.z / g.nz2) * g.ro1 + u.pm * 256 + wr * 64 + fr;
; #pragma unroll
;         for (int ai = 0; ai < 2; ++ai)
; #pragma unroll
;             for (int m = 0; m < 4; ++m) rsv[ai][m] = g.f2[rg + ai * 128 + m * 16]; }
.LBB0_346:
	s_and_b64 vcc, exec, s[6:7]
	s_cbranch_vccnz .LBB0_348
	s_ashr_i32 s0, s4, 31
	v_readlane_b32 s1, v255, 2
	s_xor_b32 s0, s0, s1
	s_abs_i32 s1, s4
	v_readlane_b32 s2, v255, 6
	s_mul_hi_u32 s2, s1, s2
	s_mul_i32 s3, s2, s79
	s_sub_i32 s1, s1, s3
	s_add_i32 s3, s2, 1
	s_sub_i32 s6, s1, s79
	s_cmp_ge_u32 s1, s79
	s_cselect_b32 s2, s3, s2
	s_cselect_b32 s1, s6, s1
	s_add_i32 s3, s2, 1
	s_cmp_ge_u32 s1, s79
	s_cselect_b32 s1, s3, s2
	s_xor_b32 s1, s1, s0
	s_sub_i32 s0, s1, s0
	v_readlane_b32 s1, v254, 59
	s_mul_i32 s0, s0, s1
	s_lshl_b32 s1, s76, 8
	s_add_i32 s0, s0, s1
	v_add_u32_e32 v2, s0, v163
	v_readlane_b32 s0, v254, 52
	v_ashrrev_i32_e32 v3, 31, v2
	v_readlane_b32 s1, v254, 53
	s_nop 1
	v_lshl_add_u64 v[2:3], v[2:3], 2, s[0:1]
	global_load_dword v164, v[2:3], off
	global_load_dword v165, v[2:3], off offset:64
	global_load_dword v166, v[2:3], off offset:128
	global_load_dword v167, v[2:3], off offset:192
	global_load_dword v168, v[2:3], off offset:512
	global_load_dword v169, v[2:3], off offset:576
	global_load_dword v170, v[2:3], off offset:640
	global_load_dword v171, v[2:3], off offset:704

; __device__ __forceinline__ void rsv_load(float (&rsv)[2][4], const GD& g, const pg8::Unit& u, int wr, int fr) {
;     if (g.f2) { const int rg = (u.z / g.nz2) * g.ro1 + u.pm * 256 + wr * 64 + fr;
; #pragma unroll
;         for (int ai = 0; ai < 2; ++ai)
; #pragma unroll
;             for (int m = 0; m < 4; ++m) rsv[ai][m] = g.f2[rg + ai * 128 + m * 16]; }
.LBB0_372:
	s_andn2_b64 vcc, exec, s[2:3]
	s_cbranch_vccnz .LBB0_484
	v_readlane_b32 s12, v254, 52
	s_ashr_i32 s5, s8, 8
	v_readlane_b32 s13, v254, 53
	v_writelane_b32 v255, s48, 18
	v_and_b32_e32 v7, 15, v194
	s_cmp_lg_u64 s[12:13], 0
	v_writelane_b32 v255, s49, 19
	s_cselect_b64 s[74:75], -1, 0
	s_cmp_eq_u64 s[12:13], 0
	s_waitcnt vmcnt(0) lgkmcnt(0)
	v_lshl_or_b32 v164, s5, 6, v7
	s_cbranch_scc1 .LBB0_375
	s_abs_i32 s2, s79
	v_cvt_f32_u32_e32 v1, s2
	s_sub_i32 s9, 0, s2
	s_xor_b32 s3, s4, s79
	s_abs_i32 s4, s4
	v_rcp_iflag_f32_e32 v1, v1
	s_ashr_i32 s3, s3, 31
	v_mul_f32_e32 v1, 0x4f7ffffe, v1
	v_cvt_u32_f32_e32 v1, v1
	s_nop 0
	v_readfirstlane_b32 s10, v1
	s_mul_i32 s9, s9, s10
	s_mul_hi_u32 s9, s10, s9
	s_add_i32 s10, s10, s9
	s_mul_hi_u32 s9, s4, s10
	s_mul_i32 s10, s9, s2
	s_sub_i32 s4, s4, s10
	s_add_i32 s11, s9, 1
	s_sub_i32 s10, s4, s2
	s_cmp_ge_u32 s4, s2
	s_cselect_b32 s9, s11, s9
	s_cselect_b32 s4, s10, s4
	s_add_i32 s10, s9, 1
	s_cmp_ge_u32 s4, s2
	s_cselect_b32 s2, s10, s9
	s_xor_b32 s2, s2, s3
	s_sub_i32 s2, s2, s3
	s_lshl_b32 s4, s1, 8
	s_mul_i32 s2, s2, s78
	s_add_i32 s2, s2, s4
	v_add_u32_e32 v2, s2, v164
	v_ashrrev_i32_e32 v3, 31, v2
	v_lshl_add_u64 v[2:3], v[2:3], 2, s[12:13]
	global_load_dword v165, v[2:3], off
	global_load_dword v166, v[2:3], off offset:64
	global_load_dword v167, v[2:3], off offset:128
	global_load_dword v168, v[2:3], off offset:192
	global_load_dword v169, v[2:3], off offset:512
	global_load_dword v170, v[2:3], off offset:576
	global_load_dword v171, v[2:3], off offset:640
	global_load_dword v172, v[2:3], off offset:704
	s_branch .LBB0_376

; template <int MODE> __device__ __forceinline__ void gemm_epilogue(f32x4 (&acc)[2][2][4][2], const GD& g, const pg8::Unit& u, int wr, int wc, int fr, int fq, LAS unsigned char* lds, const float (&rsv)[2][4]) {
;     ...
;     if (g.f2) {
; #pragma unroll
;         for (int ai = 0; ai < 2; ++ai)
; #pragma unroll
;             for (int m = 0; m < 4; ++m) { const float rs = rsqrtf(rsv[ai][m] * (1.f / DM) + EPS);
; #pragma unroll
;                 for (int bj = 0; bj < 2; ++bj)
; #pragma unroll
;                     for (int n = 0; n < 2; ++n) acc[ai][bj][m][n] = acc[ai][bj][m][n] * rs; }
;     }
.LBB0_408:
	v_cndmask_b32_e64 v1, 0, 1, s[74:75]
	v_cmp_ne_u32_e64 s[6:7], 1, v1
	s_andn2_b64 vcc, exec, s[74:75]
	s_cbranch_vccnz .LBB0_410
	s_waitcnt vmcnt(8) lgkmcnt(0)
	v_fmamk_f32 v1, v165, 0x3a000000, v203
	v_cmp_gt_f32_e32 vcc, s80, v1
	v_mul_f32_e32 v130, 0x4b800000, v1
	s_nop 0
	v_cndmask_b32_e32 v1, v1, v130, vcc
	v_rsq_f32_e32 v1, v1
	s_nop 0
	v_mul_f32_e32 v130, 0x45800000, v1
	v_cndmask_b32_e32 v130, v1, v130, vcc
	v_fmamk_f32 v1, v166, 0x3a000000, v203
	v_pk_mul_f32 v[128:129], v[130:131], v[128:129] op_sel_hi:[0,1]
	v_pk_mul_f32 v[126:127], v[130:131], v[126:127] op_sel_hi:[0,1]
	v_pk_mul_f32 v[124:125], v[130:131], v[124:125] op_sel_hi:[0,1]
	v_pk_mul_f32 v[122:123], v[130:131], v[122:123] op_sel_hi:[0,1]
	v_pk_mul_f32 v[120:121], v[130:131], v[120:121] op_sel_hi:[0,1]
	v_pk_mul_f32 v[118:119], v[130:131], v[118:119] op_sel_hi:[0,1]
	v_pk_mul_f32 v[116:117], v[130:131], v[116:117] op_sel_hi:[0,1]
	v_pk_mul_f32 v[114:115], v[130:131], v[114:115] op_sel_hi:[0,1]
	v_cmp_gt_f32_e32 vcc, s80, v1
	v_mul_f32_e32 v130, 0x4b800000, v1
	s_nop 0
	v_cndmask_b32_e32 v1, v1, v130, vcc
	v_rsq_f32_e32 v1, v1
	s_nop 0
	v_mul_f32_e32 v130, 0x45800000, v1
	v_cndmask_b32_e32 v130, v1, v130, vcc
	v_fmamk_f32 v1, v167, 0x3a000000, v203
	v_pk_mul_f32 v[112:113], v[130:131], v[112:113] op_sel_hi:[0,1]
	v_pk_mul_f32 v[110:111], v[130:131], v[110:111] op_sel_hi:[0,1]
	v_pk_mul_f32 v[108:109], v[130:131], v[108:109] op_sel_hi:[0,1]
	v_pk_mul_f32 v[106:107], v[130:131], v[106:107] op_sel_hi:[0,1]
	v_pk_mul_f32 v[104:105], v[130:131], v[104:105] op_sel_hi:[0,1]
	v_pk_mul_f32 v[102:103], v[130:131], v[102:103] op_sel_hi:[0,1]
	v_pk_mul_f32 v[100:101], v[130:131], v[100:101] op_sel_hi:[0,1]
	v_pk_mul_f32 v[98:99], v[130:131], v[98:99] op_sel_hi:[0,1]
	v_cmp_gt_f32_e32 vcc, s80, v1
	v_mul_f32_e32 v130, 0x4b800000, v1
	s_nop 0
	v_cndmask_b32_e32 v1, v1, v130, vcc
	v_rsq_f32_e32 v1, v1
	s_nop 0
	v_mul_f32_e32 v130, 0x45800000, v1
	v_cndmask_b32_e32 v130, v1, v130, vcc
	v_fmamk_f32 v1, v168, 0x3a000000, v203
	v_pk_mul_f32 v[96:97], v[130:131], v[96:97] op_sel_hi:[0,1]
	v_pk_mul_f32 v[94:95], v[130:131], v[94:95] op_sel_hi:[0,1]
	v_pk_mul_f32 v[92:93], v[130:131], v[92:93] op_sel_hi:[0,1]
	v_pk_mul_f32 v[90:91], v[130:131], v[90:91] op_sel_hi:[0,1]
	v_pk_mul_f32 v[88:89], v[130:131], v[88:89] op_sel_hi:[0,1]
	v_pk_mul_f32 v[86:87], v[130:131], v[86:87] op_sel_hi:[0,1]
	v_pk_mul_f32 v[84:85], v[130:131], v[84:85] op_sel_hi:[0,1]
	v_pk_mul_f32 v[82:83], v[130:131], v[82:83] op_sel_hi:[0,1]
	v_cmp_gt_f32_e32 vcc, s80, v1
	v_mul_f32_e32 v130, 0x4b800000, v1
	s_nop 0
	v_cndmask_b32_e32 v1, v1, v130, vcc
	v_rsq_f32_e32 v1, v1
	s_nop 0
	v_mul_f32_e32 v130, 0x45800000, v1
	v_cndmask_b32_e32 v130, v1, v130, vcc
	v_fmamk_f32 v1, v169, 0x3a000000, v203
	v_pk_mul_f32 v[80:81], v[130:131], v[80:81] op_sel_hi:[0,1]
	v_pk_mul_f32 v[78:79], v[130:131], v[78:79] op_sel_hi:[0,1]
	v_pk_mul_f32 v[76:77], v[130:131], v[76:77] op_sel_hi:[0,1]
	v_pk_mul_f32 v[74:75], v[130:131], v[74:75] op_sel_hi:[0,1]
	v_pk_mul_f32 v[72:73], v[130:131], v[72:73] op_sel_hi:[0,1]
	v_pk_mul_f32 v[70:71], v[130:131], v[70:71] op_sel_hi:[0,1]
	v_pk_mul_f32 v[68:69], v[130:131], v[68:69] op_sel_hi:[0,1]
	v_pk_mul_f32 v[66:67], v[130:131], v[66:67] op_sel_hi:[0,1]
	v_cmp_gt_f32_e32 vcc, s80, v1
	v_mul_f32_e32 v130, 0x4b800000, v1
	s_nop 0
	v_cndmask_b32_e32 v1, v1, v130, vcc
	v_rsq_f32_e32 v1, v1
	s_nop 0
	v_mul_f32_e32 v130, 0x45800000, v1
	v_cndmask_b32_e32 v130, v1, v130, vcc
	v_fmamk_f32 v1, v170, 0x3a000000, v203
	v_pk_mul_f32 v[64:65], v[130:131], v[64:65] op_sel_hi:[0,1]
	v_pk_mul_f32 v[62:63], v[130:131], v[62:63] op_sel_hi:[0,1]
	v_pk_mul_f32 v[60:61], v[130:131], v[60:61] op_sel_hi:[0,1]
	v_pk_mul_f32 v[58:59], v[130:131], v[58:59] op_sel_hi:[0,1]
	v_pk_mul_f32 v[56:57], v[130:131], v[56:57] op_sel_hi:[0,1]
	v_pk_mul_f32 v[54:55], v[130:131], v[54:55] op_sel_hi:[0,1]
	v_pk_mul_f32 v[52:53], v[130:131], v[52:53] op_sel_hi:[0,1]
	v_pk_mul_f32 v[50:51], v[130:131], v[50:51] op_sel_hi:[0,1]
	v_cmp_gt_f32_e32 vcc, s80, v1
	v_mul_f32_e32 v130, 0x4b800000, v1
	s_nop 0
	v_cndmask_b32_e32 v1, v1, v130, vcc
	v_rsq_f32_e32 v1, v1
	s_nop 0
	v_mul_f32_e32 v130, 0x45800000, v1
	v_cndmask_b32_e32 v130, v1, v130, vcc
	v_fmamk_f32 v1, v171, 0x3a000000, v203
	v_pk_mul_f32 v[48:49], v[130:131], v[48:49] op_sel_hi:[0,1]
	v_pk_mul_f32 v[46:47], v[130:131], v[46:47] op_sel_hi:[0,1]
	v_pk_mul_f32 v[44:45], v[130:131], v[44:45] op_sel_hi:[0,1]
	v_pk_mul_f32 v[42:43], v[130:131], v[42:43] op_sel_hi:[0,1]
	v_pk_mul_f32 v[40:41], v[130:131], v[40:41] op_sel_hi:[0,1]
	v_pk_mul_f32 v[38:39], v[130:131], v[38:39] op_sel_hi:[0,1]
	v_pk_mul_f32 v[36:37], v[130:131], v[36:37] op_sel_hi:[0,1]
	v_pk_mul_f32 v[34:35], v[130:131], v[34:35] op_sel_hi:[0,1]
	v_cmp_gt_f32_e32 vcc, s80, v1
	v_mul_f32_e32 v130, 0x4b800000, v1
	s_nop 0
	v_cndmask_b32_e32 v1, v1, v130, vcc
	v_rsq_f32_e32 v1, v1
	s_nop 0
	v_mul_f32_e32 v130, 0x45800000, v1
	v_cndmask_b32_e32 v130, v1, v130, vcc
	v_fmamk_f32 v1, v172, 0x3a000000, v203
	v_pk_mul_f32 v[32:33], v[130:131], v[32:33] op_sel_hi:[0,1]
	v_pk_mul_f32 v[30:31], v[130:131], v[30:31] op_sel_hi:[0,1]
	v_pk_mul_f32 v[28:29], v[130:131], v[28:29] op_sel_hi:[0,1]
	v_pk_mul_f32 v[26:27], v[130:131], v[26:27] op_sel_hi:[0,1]
	v_pk_mul_f32 v[24:25], v[130:131], v[24:25] op_sel_hi:[0,1]
	v_pk_mul_f32 v[22:23], v[130:131], v[22:23] op_sel_hi:[0,1]
	v_pk_mul_f32 v[20:21], v[130:131], v[20:21] op_sel_hi:[0,1]
	v_pk_mul_f32 v[18:19], v[130:131], v[18:19] op_sel_hi:[0,1]
	v_cmp_gt_f32_e32 vcc, s80, v1
	v_mul_f32_e32 v130, 0x4b800000, v1
	s_nop 0
	v_cndmask_b32_e32 v1, v1, v130, vcc
	v_rsq_f32_e32 v1, v1
	s_nop 0
	v_mul_f32_e32 v130, 0x45800000, v1
	v_cndmask_b32_e32 v130, v1, v130, vcc
	v_pk_mul_f32 v[16:17], v[130:131], v[16:17] op_sel_hi:[0,1]
	v_pk_mul_f32 v[14:15], v[130:131], v[14:15] op_sel_hi:[0,1]
	v_pk_mul_f32 v[12:13], v[130:131], v[12:13] op_sel_hi:[0,1]
	v_pk_mul_f32 v[10:11], v[130:131], v[10:11] op_sel_hi:[0,1]
	v_pk_mul_f32 v[8:9], v[130:131], v[8:9] op_sel_hi:[0,1]
	v_pk_mul_f32 v[6:7], v[130:131], v[6:7] op_sel_hi:[0,1]
	v_pk_mul_f32 v[4:5], v[130:131], v[4:5] op_sel_hi:[0,1]
	v_pk_mul_f32 v[2:3], v[130:131], v[2:3] op_sel_hi:[0,1]

; __device__ __forceinline__ void rsv_load(float (&rsv)[2][4], const GD& g, const pg8::Unit& u, int wr, int fr) {
;     if (g.f2) { const int rg = (u.z / g.nz2) * g.ro1 + u.pm * 256 + wr * 64 + fr;
; #pragma unroll
;         for (int ai = 0; ai < 2; ++ai)
; #pragma unroll
;             for (int m = 0; m < 4; ++m) rsv[ai][m] = g.f2[rg + ai * 128 + m * 16]; }
.LBB0_479:
	s_and_b64 vcc, exec, s[6:7]
	s_cbranch_vccnz .LBB0_481
	s_ashr_i32 s0, s31, 31
	v_readlane_b32 s1, v254, 63
	s_xor_b32 s0, s0, s1
	s_abs_i32 s1, s31
	v_readlane_b32 s2, v255, 2
	s_mul_hi_u32 s2, s1, s2
	s_mul_i32 s3, s2, s30
	s_sub_i32 s1, s1, s3
	s_add_i32 s3, s2, 1
	s_sub_i32 s6, s1, s30
	s_cmp_ge_u32 s1, s30
	s_cselect_b32 s2, s3, s2
	s_cselect_b32 s1, s6, s1
	s_add_i32 s3, s2, 1
	s_cmp_ge_u32 s1, s30
	s_cselect_b32 s1, s3, s2
	s_xor_b32 s1, s1, s0
	s_sub_i32 s0, s1, s0
	v_readlane_b32 s1, v254, 59
	s_mul_i32 s0, s0, s1
	s_lshl_b32 s1, s92, 8
	s_add_i32 s0, s0, s1
	v_add_u32_e32 v2, s0, v164
	v_readlane_b32 s0, v254, 52
	v_ashrrev_i32_e32 v3, 31, v2
	v_readlane_b32 s1, v254, 53
	s_nop 1
	v_lshl_add_u64 v[2:3], v[2:3], 2, s[0:1]
	global_load_dword v165, v[2:3], off
	global_load_dword v166, v[2:3], off offset:64
	global_load_dword v167, v[2:3], off offset:128
	global_load_dword v168, v[2:3], off offset:192
	global_load_dword v169, v[2:3], off offset:512
	global_load_dword v170, v[2:3], off offset:576
	global_load_dword v171, v[2:3], off offset:640
	global_load_dword v172, v[2:3], off offset:704

; __device__ __forceinline__ void rsv_load(float (&rsv)[2][4], const GD& g, const pg8::Unit& u, int wr, int fr) {
;     if (g.f2) { const int rg = (u.z / g.nz2) * g.ro1 + u.pm * 256 + wr * 64 + fr;
; #pragma unroll
;         for (int ai = 0; ai < 2; ++ai)
; #pragma unroll
;             for (int m = 0; m < 4; ++m) rsv[ai][m] = g.f2[rg + ai * 128 + m * 16]; }
.LBB0_505:
	s_andn2_b64 vcc, exec, s[2:3]
	s_cbranch_vccnz .LBB0_565
	v_readlane_b32 s26, v254, 52
	s_ashr_i32 s1, s0, 8
	v_readlane_b32 s27, v254, 53
	v_and_b32_e32 v7, 15, v194
	s_cmp_lg_u64 s[26:27], 0
	s_cselect_b64 s[10:11], -1, 0
	s_cmp_eq_u64 s[26:27], 0
	s_waitcnt vmcnt(0)
	v_lshl_or_b32 v144, s1, 6, v7
	s_cbranch_scc1 .LBB0_508
	s_abs_i32 s2, s79
	v_cvt_f32_u32_e32 v1, s2
	s_sub_i32 s7, 0, s2
	s_abs_i32 s6, s48
	s_xor_b32 s3, s48, s79
	v_rcp_iflag_f32_e32 v1, v1
	s_ashr_i32 s3, s3, 31
	v_mul_f32_e32 v1, 0x4f7ffffe, v1
	v_cvt_u32_f32_e32 v1, v1
	s_nop 0
	v_readfirstlane_b32 s12, v1
	s_mul_i32 s7, s7, s12
	s_mul_hi_u32 s7, s12, s7
	s_add_i32 s12, s12, s7
	s_mul_hi_u32 s7, s6, s12
	s_mul_i32 s12, s7, s2
	s_sub_i32 s6, s6, s12
	s_add_i32 s13, s7, 1
	s_sub_i32 s12, s6, s2
	s_cmp_ge_u32 s6, s2
	s_cselect_b32 s7, s13, s7
	s_cselect_b32 s6, s12, s6
	s_add_i32 s12, s7, 1
	s_cmp_ge_u32 s6, s2
	s_cselect_b32 s2, s12, s7
	s_xor_b32 s2, s2, s3
	s_sub_i32 s2, s2, s3
	s_lshl_b32 s6, s15, 8
	s_mul_i32 s2, s2, s78
	s_add_i32 s2, s2, s6
	s_waitcnt lgkmcnt(0)
	v_add_u32_e32 v2, s2, v144
	v_ashrrev_i32_e32 v3, 31, v2
	v_lshl_add_u64 v[2:3], v[2:3], 2, s[26:27]
	s_waitcnt vmcnt(0)
	global_load_dword v145, v[2:3], off
	global_load_dword v146, v[2:3], off offset:64
	global_load_dword v147, v[2:3], off offset:128
	global_load_dword v148, v[2:3], off offset:192
	global_load_dword v149, v[2:3], off offset:512
	global_load_dword v150, v[2:3], off offset:576
	global_load_dword v151, v[2:3], off offset:640
	global_load_dword v152, v[2:3], off offset:704
	s_branch .LBB0_509

; template <int MODE> __device__ __forceinline__ void gemm_epilogue(f32x4 (&acc)[2][2][4][2], const GD& g, const pg8::Unit& u, int wr, int wc, int fr, int fq, LAS unsigned char* lds, const float (&rsv)[2][4]) {
;     ...
;     if (g.f2) {
; #pragma unroll
;         for (int ai = 0; ai < 2; ++ai)
; #pragma unroll
;             for (int m = 0; m < 4; ++m) { const float rs = rsqrtf(rsv[ai][m] * (1.f / DM) + EPS);
; #pragma unroll
;                 for (int bj = 0; bj < 2; ++bj)
; #pragma unroll
;                     for (int n = 0; n < 2; ++n) acc[ai][bj][m][n] = acc[ai][bj][m][n] * rs; }
;     }
.LBB0_541:
	v_cndmask_b32_e64 v1, 0, 1, s[10:11]
	v_cmp_ne_u32_e64 s[8:9], 1, v1
	s_andn2_b64 vcc, exec, s[10:11]
	s_cbranch_vccnz .LBB0_543
	s_waitcnt vmcnt(8) lgkmcnt(0)
	v_fmamk_f32 v1, v145, 0x3a000000, v203
	v_cmp_gt_f32_e32 vcc, s80, v1
	v_mul_f32_e32 v142, 0x4b800000, v1
	s_nop 0
	v_cndmask_b32_e32 v1, v1, v142, vcc
	v_rsq_f32_e32 v1, v1
	s_nop 0
	v_mul_f32_e32 v142, 0x45800000, v1
	v_cndmask_b32_e32 v142, v1, v142, vcc
	v_fmamk_f32 v1, v146, 0x3a000000, v203
	v_pk_mul_f32 v[128:129], v[142:143], v[128:129] op_sel_hi:[0,1]
	v_pk_mul_f32 v[126:127], v[142:143], v[126:127] op_sel_hi:[0,1]
	v_pk_mul_f32 v[124:125], v[142:143], v[124:125] op_sel_hi:[0,1]
	v_pk_mul_f32 v[122:123], v[142:143], v[122:123] op_sel_hi:[0,1]
	v_pk_mul_f32 v[120:121], v[142:143], v[120:121] op_sel_hi:[0,1]
	v_pk_mul_f32 v[118:119], v[142:143], v[118:119] op_sel_hi:[0,1]
	v_pk_mul_f32 v[116:117], v[142:143], v[116:117] op_sel_hi:[0,1]
	v_pk_mul_f32 v[114:115], v[142:143], v[114:115] op_sel_hi:[0,1]
	v_cmp_gt_f32_e32 vcc, s80, v1
	v_mul_f32_e32 v142, 0x4b800000, v1
	s_nop 0
	v_cndmask_b32_e32 v1, v1, v142, vcc
	v_rsq_f32_e32 v1, v1
	s_nop 0
	v_mul_f32_e32 v142, 0x45800000, v1
	v_cndmask_b32_e32 v142, v1, v142, vcc
	v_fmamk_f32 v1, v147, 0x3a000000, v203
	v_pk_mul_f32 v[112:113], v[142:143], v[112:113] op_sel_hi:[0,1]
	v_pk_mul_f32 v[110:111], v[142:143], v[110:111] op_sel_hi:[0,1]
	v_pk_mul_f32 v[108:109], v[142:143], v[108:109] op_sel_hi:[0,1]
	v_pk_mul_f32 v[106:107], v[142:143], v[106:107] op_sel_hi:[0,1]
	v_pk_mul_f32 v[104:105], v[142:143], v[104:105] op_sel_hi:[0,1]
	v_pk_mul_f32 v[102:103], v[142:143], v[102:103] op_sel_hi:[0,1]
	v_pk_mul_f32 v[100:101], v[142:143], v[100:101] op_sel_hi:[0,1]
	v_pk_mul_f32 v[98:99], v[142:143], v[98:99] op_sel_hi:[0,1]
	v_cmp_gt_f32_e32 vcc, s80, v1
	v_mul_f32_e32 v142, 0x4b800000, v1
	s_nop 0
	v_cndmask_b32_e32 v1, v1, v142, vcc
	v_rsq_f32_e32 v1, v1
	s_nop 0
	v_mul_f32_e32 v142, 0x45800000, v1
	v_cndmask_b32_e32 v142, v1, v142, vcc
	v_fmamk_f32 v1, v148, 0x3a000000, v203
	v_pk_mul_f32 v[96:97], v[142:143], v[96:97] op_sel_hi:[0,1]
	v_pk_mul_f32 v[94:95], v[142:143], v[94:95] op_sel_hi:[0,1]
	v_pk_mul_f32 v[92:93], v[142:143], v[92:93] op_sel_hi:[0,1]
	v_pk_mul_f32 v[90:91], v[142:143], v[90:91] op_sel_hi:[0,1]
	v_pk_mul_f32 v[88:89], v[142:143], v[88:89] op_sel_hi:[0,1]
	v_pk_mul_f32 v[86:87], v[142:143], v[86:87] op_sel_hi:[0,1]
	v_pk_mul_f32 v[84:85], v[142:143], v[84:85] op_sel_hi:[0,1]
	v_pk_mul_f32 v[82:83], v[142:143], v[82:83] op_sel_hi:[0,1]
	v_cmp_gt_f32_e32 vcc, s80, v1
	v_mul_f32_e32 v142, 0x4b800000, v1
	s_nop 0
	v_cndmask_b32_e32 v1, v1, v142, vcc
	v_rsq_f32_e32 v1, v1
	s_nop 0
	v_mul_f32_e32 v142, 0x45800000, v1
	v_cndmask_b32_e32 v142, v1, v142, vcc
	v_fmamk_f32 v1, v149, 0x3a000000, v203
	v_pk_mul_f32 v[80:81], v[142:143], v[80:81] op_sel_hi:[0,1]
	v_pk_mul_f32 v[78:79], v[142:143], v[78:79] op_sel_hi:[0,1]
	v_pk_mul_f32 v[76:77], v[142:143], v[76:77] op_sel_hi:[0,1]
	v_pk_mul_f32 v[74:75], v[142:143], v[74:75] op_sel_hi:[0,1]
	v_pk_mul_f32 v[72:73], v[142:143], v[72:73] op_sel_hi:[0,1]
	v_pk_mul_f32 v[70:71], v[142:143], v[70:71] op_sel_hi:[0,1]
	v_pk_mul_f32 v[68:69], v[142:143], v[68:69] op_sel_hi:[0,1]
	v_pk_mul_f32 v[66:67], v[142:143], v[66:67] op_sel_hi:[0,1]
	v_cmp_gt_f32_e32 vcc, s80, v1
	v_mul_f32_e32 v142, 0x4b800000, v1
	s_nop 0
	v_cndmask_b32_e32 v1, v1, v142, vcc
	v_rsq_f32_e32 v1, v1
	s_nop 0
	v_mul_f32_e32 v142, 0x45800000, v1
	v_cndmask_b32_e32 v142, v1, v142, vcc
	v_fmamk_f32 v1, v150, 0x3a000000, v203
	v_pk_mul_f32 v[64:65], v[142:143], v[64:65] op_sel_hi:[0,1]
	v_pk_mul_f32 v[62:63], v[142:143], v[62:63] op_sel_hi:[0,1]
	v_pk_mul_f32 v[60:61], v[142:143], v[60:61] op_sel_hi:[0,1]
	v_pk_mul_f32 v[58:59], v[142:143], v[58:59] op_sel_hi:[0,1]
	v_pk_mul_f32 v[56:57], v[142:143], v[56:57] op_sel_hi:[0,1]
	v_pk_mul_f32 v[54:55], v[142:143], v[54:55] op_sel_hi:[0,1]
	v_pk_mul_f32 v[52:53], v[142:143], v[52:53] op_sel_hi:[0,1]
	v_pk_mul_f32 v[50:51], v[142:143], v[50:51] op_sel_hi:[0,1]
	v_cmp_gt_f32_e32 vcc, s80, v1
	v_mul_f32_e32 v142, 0x4b800000, v1
	s_nop 0
	v_cndmask_b32_e32 v1, v1, v142, vcc
	v_rsq_f32_e32 v1, v1
	s_nop 0
	v_mul_f32_e32 v142, 0x45800000, v1
	v_cndmask_b32_e32 v142, v1, v142, vcc
	v_fmamk_f32 v1, v151, 0x3a000000, v203
	v_pk_mul_f32 v[48:49], v[142:143], v[48:49] op_sel_hi:[0,1]
	v_pk_mul_f32 v[46:47], v[142:143], v[46:47] op_sel_hi:[0,1]
	v_pk_mul_f32 v[44:45], v[142:143], v[44:45] op_sel_hi:[0,1]
	v_pk_mul_f32 v[42:43], v[142:143], v[42:43] op_sel_hi:[0,1]
	v_pk_mul_f32 v[40:41], v[142:143], v[40:41] op_sel_hi:[0,1]
	v_pk_mul_f32 v[38:39], v[142:143], v[38:39] op_sel_hi:[0,1]
	v_pk_mul_f32 v[36:37], v[142:143], v[36:37] op_sel_hi:[0,1]
	v_pk_mul_f32 v[34:35], v[142:143], v[34:35] op_sel_hi:[0,1]
	v_cmp_gt_f32_e32 vcc, s80, v1
	v_mul_f32_e32 v142, 0x4b800000, v1
	s_nop 0
	v_cndmask_b32_e32 v1, v1, v142, vcc
	v_rsq_f32_e32 v1, v1
	s_nop 0
	v_mul_f32_e32 v142, 0x45800000, v1
	v_cndmask_b32_e32 v142, v1, v142, vcc
	v_fmamk_f32 v1, v152, 0x3a000000, v203
	v_pk_mul_f32 v[32:33], v[142:143], v[32:33] op_sel_hi:[0,1]
	v_pk_mul_f32 v[30:31], v[142:143], v[30:31] op_sel_hi:[0,1]
	v_pk_mul_f32 v[28:29], v[142:143], v[28:29] op_sel_hi:[0,1]
	v_pk_mul_f32 v[26:27], v[142:143], v[26:27] op_sel_hi:[0,1]
	v_pk_mul_f32 v[24:25], v[142:143], v[24:25] op_sel_hi:[0,1]
	v_pk_mul_f32 v[22:23], v[142:143], v[22:23] op_sel_hi:[0,1]
	v_pk_mul_f32 v[20:21], v[142:143], v[20:21] op_sel_hi:[0,1]
	v_pk_mul_f32 v[18:19], v[142:143], v[18:19] op_sel_hi:[0,1]
	v_cmp_gt_f32_e32 vcc, s80, v1
	v_mul_f32_e32 v142, 0x4b800000, v1
	s_nop 0
	v_cndmask_b32_e32 v1, v1, v142, vcc
	v_rsq_f32_e32 v1, v1
	s_nop 0
	v_mul_f32_e32 v142, 0x45800000, v1
	v_cndmask_b32_e32 v142, v1, v142, vcc
	v_pk_mul_f32 v[16:17], v[142:143], v[16:17] op_sel_hi:[0,1]
	v_pk_mul_f32 v[14:15], v[142:143], v[14:15] op_sel_hi:[0,1]
	v_pk_mul_f32 v[12:13], v[142:143], v[12:13] op_sel_hi:[0,1]
	v_pk_mul_f32 v[10:11], v[142:143], v[10:11] op_sel_hi:[0,1]
	v_pk_mul_f32 v[8:9], v[142:143], v[8:9] op_sel_hi:[0,1]
	v_pk_mul_f32 v[6:7], v[142:143], v[6:7] op_sel_hi:[0,1]
	v_pk_mul_f32 v[4:5], v[142:143], v[4:5] op_sel_hi:[0,1]
	v_pk_mul_f32 v[2:3], v[142:143], v[2:3] op_sel_hi:[0,1]

; #define LAS __attribute__((address_space(3)))
; __device__ __forceinline__ unsigned cvt_pk_bf16(float lo, float hi) { f32x2 v = {lo, hi}; bf16x2_t b = __builtin_convertvector(v, bf16x2_t); return __builtin_bit_cast(unsigned, b); }
; #define WG_BAR() do { asm volatile("s_waitcnt lgkmcnt(0)" ::: "memory"); __builtin_amdgcn_s_barrier(); asm volatile("" ::: "memory"); } while (0)
; template <int MODE> __device__ __forceinline__ void gemm_epilogue(f32x4 (&acc)[2][2][4][2], const GD& g, const pg8::Unit& u, int wr, int wc, int fr, int fq, LAS unsigned char* lds, const float (&rsv)[2][4]) {
;     ...
;         WG_BAR();
;         const int z1 = u.z / g.nz2, z2 = u.z % g.nz2;
;         const int row0 = z1 * g.ro1 + rt, col0 = z2 * g.co2 + u.pn * 256 + ct;
;         bf16_t* O = (bf16_t*)g.o0;
; #pragma unroll
;         for (int ai = 0; ai < 2; ++ai)
; #pragma unroll
;             for (int m = 0; m < 4; ++m) { const f32x4 t = *(const LAS f32x4*)(red + (ai * 128 + wr * 64 + m * 16 + fr) * 4); const float inv = 1.f / ((t[0] + t[1]) + (t[2] + t[3]));
;                 bf16_t* rowp = O + (size_t)(row0 + ai * 128 + m * 16) * g.ldc + col0;
; #pragma unroll
;                 for (int bj = 0; bj < 2; ++bj) { const f32x4 v0 = acc[ai][bj][m][0] * inv, v1 = acc[ai][bj][m][1] * inv;
;                     u32x4 w; w.x = cvt_pk_bf16(v0[0], v0[1]); w.y = cvt_pk_bf16(v0[2], v0[3]); w.z = cvt_pk_bf16(v1[0], v1[1]); w.w = cvt_pk_bf16(v1[2], v1[3]);
;                     *(u32x4*)(rowp + bj * 128) = w; } }
.LBB0_559:
	s_or_b64 exec, exec, s[2:3]
	s_abs_i32 s12, s48
	s_mul_hi_u32 s13, s12, s56
	s_lshl_b32 s2, s15, 8
	s_mul_i32 s15, s13, s18
	s_ashr_i32 s3, s48, 31
	s_sub_i32 s12, s12, s15
	s_xor_b32 s3, s3, s57
	s_add_i32 s15, s13, 1
	s_sub_i32 s35, s12, s18
	s_cmp_ge_u32 s12, s18
	v_add_u32_e32 v1, 0, v154
	s_waitcnt lgkmcnt(0)
	s_barrier
	s_cselect_b32 s13, s15, s13
	v_add_u32_e32 v158, 0x20000, v1
	s_cselect_b32 s12, s35, s12
	s_add_i32 s15, s13, 1
	ds_read_b128 v[160:163], v158
	s_cmp_ge_u32 s12, s18
	s_cselect_b32 s12, s15, s13
	s_xor_b32 s12, s12, s3
	s_sub_i32 s3, s12, s3
	s_mul_i32 s12, s3, s79
	s_waitcnt lgkmcnt(0)
	v_mov_b32_e32 v164, v161
	v_mov_b32_e32 v165, v162
	v_mov_b32_e32 v161, v163
	s_sub_i32 s12, s48, s12
	v_readlane_b32 s13, v254, 50
	v_pk_add_f32 v[160:161], v[164:165], v[160:161]
	s_mul_i32 s3, s3, s78
	s_mul_i32 s12, s12, s13
	v_lshl_or_b32 v1, s14, 8, v155
	v_add_f32_e32 v159, v160, v161
	v_add_u32_e32 v142, s12, v1
	s_add_i32 s12, s3, s2
	v_div_scale_f32 v160, s[2:3], v159, v159, 1.0
	v_rcp_f32_e32 v161, v160
	v_readlane_b32 s2, v254, 42
	v_add_u32_e32 v1, s12, v144
	v_ashrrev_i32_e32 v143, 31, v142
	v_fma_f32 v162, -v160, v161, 1.0
	v_fmac_f32_e32 v161, v162, v161
	v_div_scale_f32 v162, vcc, 1.0, v159, 1.0
	v_mul_f32_e32 v163, v162, v161
	v_fma_f32 v164, -v160, v163, v162
	v_fmac_f32_e32 v163, v164, v161
	v_fma_f32 v160, -v160, v163, v162
	v_div_fmas_f32 v160, v160, v161, v163
	v_readlane_b32 s3, v254, 43
	v_div_fixup_f32 v160, v160, v159, 1.0
	v_pk_mul_f32 v[128:129], v[128:129], v[160:161] op_sel_hi:[1,0]
	v_lshl_add_u64 v[142:143], v[142:143], 1, s[2:3]
	v_mad_i64_i32 v[162:163], s[2:3], v1, s19, 0
	v_pk_mul_f32 v[126:127], v[126:127], v[160:161] op_sel_hi:[1,0]
	v_pk_mul_f32 v[164:165], v[124:125], v[160:161] op_sel_hi:[1,0]
	v_pk_mul_f32 v[124:125], v[122:123], v[160:161] op_sel_hi:[1,0]
	v_lshl_add_u64 v[162:163], v[162:163], 1, v[142:143]
	v_cvt_pk_bf16_f32 v122, v126, v127
	v_cvt_pk_bf16_f32 v123, v128, v129
	v_cvt_pk_bf16_f32 v124, v124, v125
	v_cvt_pk_bf16_f32 v125, v164, v165
	flat_store_dwordx4 v[162:163], v[122:125]
	v_pk_mul_f32 v[120:121], v[120:121], v[160:161] op_sel_hi:[1,0]
	v_pk_mul_f32 v[118:119], v[118:119], v[160:161] op_sel_hi:[1,0]
	v_pk_mul_f32 v[122:123], v[116:117], v[160:161] op_sel_hi:[1,0]
	v_pk_mul_f32 v[116:117], v[114:115], v[160:161] op_sel_hi:[1,0]
	v_cvt_pk_bf16_f32 v114, v118, v119
	v_cvt_pk_bf16_f32 v115, v120, v121
	v_cvt_pk_bf16_f32 v116, v116, v117
	v_cvt_pk_bf16_f32 v117, v122, v123
	flat_store_dwordx4 v[162:163], v[114:117] offset:256
	ds_read_b128 v[114:117], v158 offset:256
	s_waitcnt lgkmcnt(0)
	v_mov_b32_e32 v118, v115
	v_mov_b32_e32 v119, v116
	v_mov_b32_e32 v115, v117
	v_pk_add_f32 v[114:115], v[118:119], v[114:115]
	s_nop 0
	v_add_f32_e32 v114, v114, v115
	v_div_scale_f32 v115, s[2:3], v114, v114, 1.0
	v_rcp_f32_e32 v116, v115
	s_nop 0
	v_fma_f32 v117, -v115, v116, 1.0
	v_fmac_f32_e32 v116, v117, v116
	v_div_scale_f32 v117, vcc, 1.0, v114, 1.0
	v_mul_f32_e32 v118, v117, v116
	v_fma_f32 v119, -v115, v118, v117
	v_fmac_f32_e32 v118, v119, v116
	v_fma_f32 v115, -v115, v118, v117
	v_div_fmas_f32 v115, v115, v116, v118
	v_div_fixup_f32 v114, v115, v114, 1.0
	v_add_u32_e32 v115, 16, v1
	v_mad_i64_i32 v[116:117], s[2:3], v115, s19, 0
	v_pk_mul_f32 v[112:113], v[112:113], v[114:115] op_sel_hi:[1,0]
	v_pk_mul_f32 v[110:111], v[110:111], v[114:115] op_sel_hi:[1,0]
	v_pk_mul_f32 v[118:119], v[108:109], v[114:115] op_sel_hi:[1,0]
	v_pk_mul_f32 v[108:109], v[106:107], v[114:115] op_sel_hi:[1,0]
	v_lshl_add_u64 v[116:117], v[116:117], 1, v[142:143]
	v_cvt_pk_bf16_f32 v106, v110, v111
	v_cvt_pk_bf16_f32 v107, v112, v113
	v_cvt_pk_bf16_f32 v108, v108, v109
	v_cvt_pk_bf16_f32 v109, v118, v119
	flat_store_dwordx4 v[116:117], v[106:109]
	v_pk_mul_f32 v[104:105], v[104:105], v[114:115] op_sel_hi:[1,0]
	v_pk_mul_f32 v[102:103], v[102:103], v[114:115] op_sel_hi:[1,0]
	v_pk_mul_f32 v[106:107], v[100:101], v[114:115] op_sel_hi:[1,0]
	v_pk_mul_f32 v[100:101], v[98:99], v[114:115] op_sel_hi:[1,0]
	v_cvt_pk_bf16_f32 v98, v102, v103
	v_cvt_pk_bf16_f32 v99, v104, v105
	v_cvt_pk_bf16_f32 v100, v100, v101
	v_cvt_pk_bf16_f32 v101, v106, v107
	flat_store_dwordx4 v[116:117], v[98:101] offset:256
	ds_read_b128 v[98:101], v158 offset:512
	s_waitcnt lgkmcnt(0)
	v_mov_b32_e32 v102, v99
	v_mov_b32_e32 v103, v100
	v_mov_b32_e32 v99, v101
	v_pk_add_f32 v[98:99], v[102:103], v[98:99]
	s_nop 0
	v_add_f32_e32 v98, v98, v99
	v_div_scale_f32 v99, s[2:3], v98, v98, 1.0
	v_rcp_f32_e32 v100, v99
	s_nop 0
	v_fma_f32 v101, -v99, v100, 1.0
	v_fmac_f32_e32 v100, v101, v100
	v_div_scale_f32 v101, vcc, 1.0, v98, 1.0
	v_mul_f32_e32 v102, v101, v100
	v_fma_f32 v103, -v99, v102, v101
	v_fmac_f32_e32 v102, v103, v100
	v_fma_f32 v99, -v99, v102, v101
	v_div_fmas_f32 v99, v99, v100, v102
	v_div_fixup_f32 v98, v99, v98, 1.0
	v_add_u32_e32 v99, 32, v1
	v_mad_i64_i32 v[100:101], s[2:3], v99, s19, 0
	v_pk_mul_f32 v[96:97], v[96:97], v[98:99] op_sel_hi:[1,0]
	v_pk_mul_f32 v[94:95], v[94:95], v[98:99] op_sel_hi:[1,0]
	v_pk_mul_f32 v[102:103], v[92:93], v[98:99] op_sel_hi:[1,0]
	v_pk_mul_f32 v[92:93], v[90:91], v[98:99] op_sel_hi:[1,0]
	v_lshl_add_u64 v[100:101], v[100:101], 1, v[142:143]
	v_cvt_pk_bf16_f32 v90, v94, v95
	v_cvt_pk_bf16_f32 v91, v96, v97
	v_cvt_pk_bf16_f32 v92, v92, v93
	v_cvt_pk_bf16_f32 v93, v102, v103
	flat_store_dwordx4 v[100:101], v[90:93]
	v_pk_mul_f32 v[88:89], v[88:89], v[98:99] op_sel_hi:[1,0]
	v_pk_mul_f32 v[86:87], v[86:87], v[98:99] op_sel_hi:[1,0]
	v_pk_mul_f32 v[90:91], v[84:85], v[98:99] op_sel_hi:[1,0]
	v_pk_mul_f32 v[84:85], v[82:83], v[98:99] op_sel_hi:[1,0]
	v_cvt_pk_bf16_f32 v82, v86, v87
	v_cvt_pk_bf16_f32 v83, v88, v89
	v_cvt_pk_bf16_f32 v84, v84, v85
	v_cvt_pk_bf16_f32 v85, v90, v91
	flat_store_dwordx4 v[100:101], v[82:85] offset:256
	ds_read_b128 v[82:85], v158 offset:768
	s_waitcnt lgkmcnt(0)
; #define LAS __attribute__((address_space(3)))
; __device__ __forceinline__ unsigned cvt_pk_bf16(float lo, float hi) { f32x2 v = {lo, hi}; bf16x2_t b = __builtin_convertvector(v, bf16x2_t); return __builtin_bit_cast(unsigned, b); }
; #define WG_BAR() do { asm volatile("s_waitcnt lgkmcnt(0)" ::: "memory"); __builtin_amdgcn_s_barrier(); asm volatile("" ::: "memory"); } while (0)
; template <int MODE> __device__ __forceinline__ void gemm_epilogue(f32x4 (&acc)[2][2][4][2], const GD& g, const pg8::Unit& u, int wr, int wc, int fr, int fq, LAS unsigned char* lds, const float (&rsv)[2][4]) {
;     ...
;         WG_BAR();
;         const int z1 = u.z / g.nz2, z2 = u.z % g.nz2;
;         const int row0 = z1 * g.ro1 + rt, col0 = z2 * g.co2 + u.pn * 256 + ct;
;         bf16_t* O = (bf16_t*)g.o0;
; #pragma unroll
;         for (int ai = 0; ai < 2; ++ai)
; #pragma unroll
;             for (int m = 0; m < 4; ++m) { const f32x4 t = *(const LAS f32x4*)(red + (ai * 128 + wr * 64 + m * 16 + fr) * 4); const float inv = 1.f / ((t[0] + t[1]) + (t[2] + t[3]));
;                 bf16_t* rowp = O + (size_t)(row0 + ai * 128 + m * 16) * g.ldc + col0;
; #pragma unroll
;                 for (int bj = 0; bj < 2; ++bj) { const f32x4 v0 = acc[ai][bj][m][0] * inv, v1 = acc[ai][bj][m][1] * inv;
;                     u32x4 w; w.x = cvt_pk_bf16(v0[0], v0[1]); w.y = cvt_pk_bf16(v0[2], v0[3]); w.z = cvt_pk_bf16(v1[0], v1[1]); w.w = cvt_pk_bf16(v1[2], v1[3]);
;                     *(u32x4*)(rowp + bj * 128) = w; } }
	v_mov_b32_e32 v86, v83
	v_mov_b32_e32 v87, v84
	v_mov_b32_e32 v83, v85
	v_pk_add_f32 v[82:83], v[86:87], v[82:83]
	s_nop 0
	v_add_f32_e32 v82, v82, v83
	v_div_scale_f32 v83, s[2:3], v82, v82, 1.0
	v_rcp_f32_e32 v84, v83
	s_nop 0
	v_fma_f32 v85, -v83, v84, 1.0
	v_fmac_f32_e32 v84, v85, v84
	v_div_scale_f32 v85, vcc, 1.0, v82, 1.0
	v_mul_f32_e32 v86, v85, v84
	v_fma_f32 v87, -v83, v86, v85
	v_fmac_f32_e32 v86, v87, v84
	v_fma_f32 v83, -v83, v86, v85
	v_div_fmas_f32 v83, v83, v84, v86
	v_div_fixup_f32 v82, v83, v82, 1.0
	v_add_u32_e32 v83, 48, v1
	v_mad_i64_i32 v[84:85], s[2:3], v83, s19, 0
	v_pk_mul_f32 v[80:81], v[80:81], v[82:83] op_sel_hi:[1,0]
	v_pk_mul_f32 v[78:79], v[78:79], v[82:83] op_sel_hi:[1,0]
	v_pk_mul_f32 v[86:87], v[76:77], v[82:83] op_sel_hi:[1,0]
	v_pk_mul_f32 v[76:77], v[74:75], v[82:83] op_sel_hi:[1,0]
	v_lshl_add_u64 v[84:85], v[84:85], 1, v[142:143]
	v_cvt_pk_bf16_f32 v74, v78, v79
	v_cvt_pk_bf16_f32 v75, v80, v81
	v_cvt_pk_bf16_f32 v76, v76, v77
	v_cvt_pk_bf16_f32 v77, v86, v87
	flat_store_dwordx4 v[84:85], v[74:77]
	v_pk_mul_f32 v[72:73], v[72:73], v[82:83] op_sel_hi:[1,0]
	v_pk_mul_f32 v[70:71], v[70:71], v[82:83] op_sel_hi:[1,0]
	v_pk_mul_f32 v[74:75], v[68:69], v[82:83] op_sel_hi:[1,0]
	v_pk_mul_f32 v[68:69], v[66:67], v[82:83] op_sel_hi:[1,0]
	v_cvt_pk_bf16_f32 v66, v70, v71
	v_cvt_pk_bf16_f32 v67, v72, v73
	v_cvt_pk_bf16_f32 v68, v68, v69
	v_cvt_pk_bf16_f32 v69, v74, v75
	flat_store_dwordx4 v[84:85], v[66:69] offset:256
	ds_read_b128 v[66:69], v158 offset:2048
	s_waitcnt lgkmcnt(0)
	v_mov_b32_e32 v70, v67
	v_mov_b32_e32 v71, v68
	v_mov_b32_e32 v67, v69
	v_pk_add_f32 v[66:67], v[70:71], v[66:67]
	v_add_u32_e32 v69, 0x80, v1
	v_add_f32_e32 v66, v66, v67
	v_div_scale_f32 v67, s[2:3], v66, v66, 1.0
	v_rcp_f32_e32 v68, v67
	s_nop 0
	v_fma_f32 v70, -v67, v68, 1.0
	v_fmac_f32_e32 v68, v70, v68
	v_div_scale_f32 v70, vcc, 1.0, v66, 1.0
	v_mul_f32_e32 v71, v70, v68
	v_fma_f32 v72, -v67, v71, v70
	v_fmac_f32_e32 v71, v72, v68
	v_fma_f32 v67, -v67, v71, v70
	v_div_fmas_f32 v67, v67, v68, v71
	v_div_fixup_f32 v66, v67, v66, 1.0
	v_mad_i64_i32 v[68:69], s[2:3], v69, s19, 0
	v_pk_mul_f32 v[64:65], v[64:65], v[66:67] op_sel_hi:[1,0]
	v_pk_mul_f32 v[62:63], v[62:63], v[66:67] op_sel_hi:[1,0]
	v_pk_mul_f32 v[70:71], v[60:61], v[66:67] op_sel_hi:[1,0]
	v_pk_mul_f32 v[60:61], v[58:59], v[66:67] op_sel_hi:[1,0]
	v_lshl_add_u64 v[68:69], v[68:69], 1, v[142:143]
	v_cvt_pk_bf16_f32 v58, v62, v63
	v_cvt_pk_bf16_f32 v59, v64, v65
	v_cvt_pk_bf16_f32 v60, v60, v61
	v_cvt_pk_bf16_f32 v61, v70, v71
	flat_store_dwordx4 v[68:69], v[58:61]
	v_pk_mul_f32 v[56:57], v[56:57], v[66:67] op_sel_hi:[1,0]
	v_pk_mul_f32 v[54:55], v[54:55], v[66:67] op_sel_hi:[1,0]
	v_pk_mul_f32 v[58:59], v[52:53], v[66:67] op_sel_hi:[1,0]
	v_pk_mul_f32 v[52:53], v[50:51], v[66:67] op_sel_hi:[1,0]
	v_cvt_pk_bf16_f32 v50, v54, v55
	v_cvt_pk_bf16_f32 v51, v56, v57
	v_cvt_pk_bf16_f32 v52, v52, v53
	v_cvt_pk_bf16_f32 v53, v58, v59
	flat_store_dwordx4 v[68:69], v[50:53] offset:256
	ds_read_b128 v[50:53], v158 offset:2304
	s_waitcnt lgkmcnt(0)
	v_mov_b32_e32 v54, v51
	v_mov_b32_e32 v55, v52
	v_mov_b32_e32 v51, v53
	v_pk_add_f32 v[50:51], v[54:55], v[50:51]
	s_nop 0
	v_add_f32_e32 v50, v50, v51
	v_div_scale_f32 v51, s[2:3], v50, v50, 1.0
	v_rcp_f32_e32 v52, v51
	s_nop 0
	v_fma_f32 v53, -v51, v52, 1.0
	v_fmac_f32_e32 v52, v53, v52
	v_div_scale_f32 v53, vcc, 1.0, v50, 1.0
	v_mul_f32_e32 v54, v53, v52
	v_fma_f32 v55, -v51, v54, v53
	v_fmac_f32_e32 v54, v55, v52
	v_fma_f32 v51, -v51, v54, v53
	v_div_fmas_f32 v51, v51, v52, v54
	v_div_fixup_f32 v50, v51, v50, 1.0
	v_add_u32_e32 v51, 0x90, v1
	v_mad_i64_i32 v[52:53], s[2:3], v51, s19, 0
	v_pk_mul_f32 v[48:49], v[48:49], v[50:51] op_sel_hi:[1,0]
	v_pk_mul_f32 v[46:47], v[46:47], v[50:51] op_sel_hi:[1,0]
	v_pk_mul_f32 v[54:55], v[44:45], v[50:51] op_sel_hi:[1,0]
	v_pk_mul_f32 v[44:45], v[42:43], v[50:51] op_sel_hi:[1,0]
	v_lshl_add_u64 v[52:53], v[52:53], 1, v[142:143]
	v_cvt_pk_bf16_f32 v42, v46, v47
	v_cvt_pk_bf16_f32 v43, v48, v49
	v_cvt_pk_bf16_f32 v44, v44, v45
	v_cvt_pk_bf16_f32 v45, v54, v55
	flat_store_dwordx4 v[52:53], v[42:45]
	v_pk_mul_f32 v[40:41], v[40:41], v[50:51] op_sel_hi:[1,0]
	v_pk_mul_f32 v[38:39], v[38:39], v[50:51] op_sel_hi:[1,0]
	v_pk_mul_f32 v[42:43], v[36:37], v[50:51] op_sel_hi:[1,0]
	v_pk_mul_f32 v[36:37], v[34:35], v[50:51] op_sel_hi:[1,0]
	v_cvt_pk_bf16_f32 v34, v38, v39
	v_cvt_pk_bf16_f32 v35, v40, v41
	v_cvt_pk_bf16_f32 v36, v36, v37
	v_cvt_pk_bf16_f32 v37, v42, v43
	flat_store_dwordx4 v[52:53], v[34:37] offset:256
	ds_read_b128 v[34:37], v158 offset:2560
	s_waitcnt lgkmcnt(0)
; #define LAS __attribute__((address_space(3)))
; __device__ __forceinline__ unsigned cvt_pk_bf16(float lo, float hi) { f32x2 v = {lo, hi}; bf16x2_t b = __builtin_convertvector(v, bf16x2_t); return __builtin_bit_cast(unsigned, b); }
; #define WG_BAR() do { asm volatile("s_waitcnt lgkmcnt(0)" ::: "memory"); __builtin_amdgcn_s_barrier(); asm volatile("" ::: "memory"); } while (0)
; template <int MODE> __device__ __forceinline__ void gemm_epilogue(f32x4 (&acc)[2][2][4][2], const GD& g, const pg8::Unit& u, int wr, int wc, int fr, int fq, LAS unsigned char* lds, const float (&rsv)[2][4]) {
;     ...
;             for (int m = 0; m < 4; ++m) { const f32x4 t = *(const LAS f32x4*)(red + (ai * 128 + wr * 64 + m * 16 + fr) * 4); const float inv = 1.f / ((t[0] + t[1]) + (t[2] + t[3]));
;                 bf16_t* rowp = O + (size_t)(row0 + ai * 128 + m * 16) * g.ldc + col0;
; #pragma unroll
;                 for (int bj = 0; bj < 2; ++bj) { const f32x4 v0 = acc[ai][bj][m][0] * inv, v1 = acc[ai][bj][m][1] * inv;
;                     u32x4 w; w.x = cvt_pk_bf16(v0[0], v0[1]); w.y = cvt_pk_bf16(v0[2], v0[3]); w.z = cvt_pk_bf16(v1[0], v1[1]); w.w = cvt_pk_bf16(v1[2], v1[3]);
;                     *(u32x4*)(rowp + bj * 128) = w; } }
;         WG_BAR();
; __device__ __forceinline__ void rsv_load(float (&rsv)[2][4], const GD& g, const pg8::Unit& u, int wr, int fr) {
;     if (g.f2) { const int rg = (u.z / g.nz2) * g.ro1 + u.pm * 256 + wr * 64 + fr;
; #pragma unroll
;         for (int ai = 0; ai < 2; ++ai)
; #pragma unroll
;             for (int m = 0; m < 4; ++m) rsv[ai][m] = g.f2[rg + ai * 128 + m * 16]; }
	v_mov_b32_e32 v38, v35
	v_mov_b32_e32 v39, v36
	v_mov_b32_e32 v35, v37
	v_pk_add_f32 v[34:35], v[38:39], v[34:35]
	s_nop 0
	v_add_f32_e32 v34, v34, v35
	v_div_scale_f32 v35, s[2:3], v34, v34, 1.0
	v_rcp_f32_e32 v36, v35
	s_nop 0
	v_fma_f32 v37, -v35, v36, 1.0
	v_fmac_f32_e32 v36, v37, v36
	v_div_scale_f32 v37, vcc, 1.0, v34, 1.0
	v_mul_f32_e32 v38, v37, v36
	v_fma_f32 v39, -v35, v38, v37
	v_fmac_f32_e32 v38, v39, v36
	v_fma_f32 v35, -v35, v38, v37
	v_div_fmas_f32 v35, v35, v36, v38
	v_div_fixup_f32 v34, v35, v34, 1.0
	v_add_u32_e32 v35, 0xa0, v1
	v_mad_i64_i32 v[36:37], s[2:3], v35, s19, 0
	v_pk_mul_f32 v[32:33], v[32:33], v[34:35] op_sel_hi:[1,0]
	v_pk_mul_f32 v[30:31], v[30:31], v[34:35] op_sel_hi:[1,0]
	v_pk_mul_f32 v[38:39], v[28:29], v[34:35] op_sel_hi:[1,0]
	v_pk_mul_f32 v[28:29], v[26:27], v[34:35] op_sel_hi:[1,0]
	v_lshl_add_u64 v[36:37], v[36:37], 1, v[142:143]
	v_cvt_pk_bf16_f32 v26, v30, v31
	v_cvt_pk_bf16_f32 v27, v32, v33
	v_cvt_pk_bf16_f32 v28, v28, v29
	v_cvt_pk_bf16_f32 v29, v38, v39
	flat_store_dwordx4 v[36:37], v[26:29]
	v_pk_mul_f32 v[24:25], v[24:25], v[34:35] op_sel_hi:[1,0]
	v_pk_mul_f32 v[22:23], v[22:23], v[34:35] op_sel_hi:[1,0]
	v_pk_mul_f32 v[26:27], v[20:21], v[34:35] op_sel_hi:[1,0]
	v_pk_mul_f32 v[20:21], v[18:19], v[34:35] op_sel_hi:[1,0]
	v_cvt_pk_bf16_f32 v18, v22, v23
	v_cvt_pk_bf16_f32 v19, v24, v25
	v_cvt_pk_bf16_f32 v20, v20, v21
	v_cvt_pk_bf16_f32 v21, v26, v27
	flat_store_dwordx4 v[36:37], v[18:21] offset:256
	ds_read_b128 v[18:21], v158 offset:2816
	v_add_u32_e32 v1, 0xb0, v1
	s_waitcnt lgkmcnt(0)
	v_mov_b32_e32 v22, v19
	v_mov_b32_e32 v23, v20
	v_mov_b32_e32 v19, v21
	v_pk_add_f32 v[18:19], v[22:23], v[18:19]
	s_nop 0
	v_add_f32_e32 v18, v18, v19
	v_div_scale_f32 v19, s[2:3], v18, v18, 1.0
	v_rcp_f32_e32 v20, v19
	s_nop 0
	v_fma_f32 v21, -v19, v20, 1.0
	v_fmac_f32_e32 v20, v21, v20
	v_div_scale_f32 v21, vcc, 1.0, v18, 1.0
	v_mul_f32_e32 v22, v21, v20
	v_fma_f32 v23, -v19, v22, v21
	v_fmac_f32_e32 v22, v23, v20
	v_fma_f32 v19, -v19, v22, v21
	v_div_fmas_f32 v19, v19, v20, v22
	v_div_fixup_f32 v18, v19, v18, 1.0
	v_mad_i64_i32 v[20:21], s[2:3], v1, s19, 0
	v_pk_mul_f32 v[16:17], v[16:17], v[18:19] op_sel_hi:[1,0]
	v_pk_mul_f32 v[14:15], v[14:15], v[18:19] op_sel_hi:[1,0]
	v_pk_mul_f32 v[22:23], v[12:13], v[18:19] op_sel_hi:[1,0]
	v_pk_mul_f32 v[12:13], v[10:11], v[18:19] op_sel_hi:[1,0]
	v_lshl_add_u64 v[20:21], v[20:21], 1, v[142:143]
	v_cvt_pk_bf16_f32 v10, v14, v15
	v_cvt_pk_bf16_f32 v11, v16, v17
	v_cvt_pk_bf16_f32 v12, v12, v13
	v_cvt_pk_bf16_f32 v13, v22, v23
	flat_store_dwordx4 v[20:21], v[10:13]
	v_pk_mul_f32 v[8:9], v[8:9], v[18:19] op_sel_hi:[1,0]
	v_pk_mul_f32 v[6:7], v[6:7], v[18:19] op_sel_hi:[1,0]
	v_pk_mul_f32 v[10:11], v[4:5], v[18:19] op_sel_hi:[1,0]
	v_pk_mul_f32 v[4:5], v[2:3], v[18:19] op_sel_hi:[1,0]
	v_cvt_pk_bf16_f32 v2, v6, v7
	v_cvt_pk_bf16_f32 v3, v8, v9
	v_cvt_pk_bf16_f32 v4, v4, v5
	v_cvt_pk_bf16_f32 v5, v10, v11
	flat_store_dwordx4 v[20:21], v[2:5] offset:256
	s_waitcnt lgkmcnt(0)
	s_barrier
	s_andn2_b64 vcc, exec, s[74:75]
	s_mov_b64 s[2:3], -1
	s_cbranch_vccnz .LBB0_513
	s_and_b64 vcc, exec, s[8:9]
	s_cbranch_vccnz .LBB0_562
	s_abs_i32 s3, s33
	s_mul_hi_u32 s8, s3, s56
	s_mul_i32 s9, s8, s18
	s_ashr_i32 s2, s33, 31
	s_sub_i32 s3, s3, s9
	s_xor_b32 s2, s2, s57
	s_add_i32 s9, s8, 1
	s_sub_i32 s12, s3, s18
	s_cmp_ge_u32 s3, s18
	s_cselect_b32 s8, s9, s8
	s_cselect_b32 s3, s12, s3
	s_add_i32 s9, s8, 1
	s_cmp_ge_u32 s3, s18
	s_cselect_b32 s3, s9, s8
	s_xor_b32 s3, s3, s2
	s_sub_i32 s2, s3, s2
	s_mul_i32 s2, s2, s78
	s_lshl_b32 s3, s46, 8
	s_add_i32 s2, s2, s3
	v_add_u32_e32 v2, s2, v144
	v_readlane_b32 s2, v254, 52
	v_ashrrev_i32_e32 v3, 31, v2
	v_readlane_b32 s3, v254, 53
	s_nop 1
	v_lshl_add_u64 v[2:3], v[2:3], 2, s[2:3]
	s_waitcnt vmcnt(0)
	global_load_dword v145, v[2:3], off
	global_load_dword v146, v[2:3], off offset:64
	global_load_dword v147, v[2:3], off offset:128
	global_load_dword v148, v[2:3], off offset:192
	global_load_dword v149, v[2:3], off offset:512
	global_load_dword v150, v[2:3], off offset:576
	global_load_dword v151, v[2:3], off offset:640
	global_load_dword v152, v[2:3], off offset:704

; __device__ __forceinline__ void rsv_load(float (&rsv)[2][4], const GD& g, const pg8::Unit& u, int wr, int fr) {
;     if (g.f2) { const int rg = (u.z / g.nz2) * g.ro1 + u.pm * 256 + wr * 64 + fr;
; #pragma unroll
;         for (int ai = 0; ai < 2; ++ai)
; #pragma unroll
;             for (int m = 0; m < 4; ++m) rsv[ai][m] = g.f2[rg + ai * 128 + m * 16]; }
.LBB0_584:
	s_andn2_b64 vcc, exec, s[2:3]
	s_cbranch_vccnz .LBB0_636
	v_readlane_b32 s14, v254, 52
	s_ashr_i32 s9, s8, 8
	v_readlane_b32 s15, v254, 53
	v_and_b32_e32 v7, 15, v194
	s_cmp_lg_u64 s[14:15], 0
	s_cselect_b64 s[10:11], -1, 0
	s_cmp_eq_u64 s[14:15], 0
	s_waitcnt vmcnt(0) lgkmcnt(0)
	v_lshl_or_b32 v162, s9, 6, v7
	s_cbranch_scc1 .LBB0_587
	s_abs_i32 s0, s79
	v_cvt_f32_u32_e32 v1, s0
	s_sub_i32 s3, 0, s0
	s_abs_i32 s2, s95
	s_xor_b32 s1, s95, s79
	v_rcp_iflag_f32_e32 v1, v1
	s_ashr_i32 s1, s1, 31
	v_mul_f32_e32 v1, 0x4f7ffffe, v1
	v_cvt_u32_f32_e32 v1, v1
	s_nop 0
	v_readfirstlane_b32 s12, v1
	s_mul_i32 s3, s3, s12
	s_mul_hi_u32 s3, s12, s3
	s_add_i32 s12, s12, s3
	s_mul_hi_u32 s3, s2, s12
	s_mul_i32 s12, s3, s0
	s_sub_i32 s2, s2, s12
	s_add_i32 s13, s3, 1
	s_sub_i32 s12, s2, s0
	s_cmp_ge_u32 s2, s0
	s_cselect_b32 s3, s13, s3
	s_cselect_b32 s2, s12, s2
	s_add_i32 s12, s3, 1
	s_cmp_ge_u32 s2, s0
	s_cselect_b32 s0, s12, s3
	s_xor_b32 s0, s0, s1
	s_sub_i32 s0, s0, s1
	s_lshl_b32 s2, s38, 8
	s_mul_i32 s0, s0, s78
	s_add_i32 s0, s0, s2
	v_add_u32_e32 v2, s0, v162
	v_ashrrev_i32_e32 v3, 31, v2
	v_lshl_add_u64 v[2:3], v[2:3], 2, s[14:15]
	global_load_dword v163, v[2:3], off
	global_load_dword v164, v[2:3], off offset:64
	global_load_dword v165, v[2:3], off offset:128
	global_load_dword v166, v[2:3], off offset:192
	global_load_dword v167, v[2:3], off offset:512
	global_load_dword v168, v[2:3], off offset:576
	global_load_dword v169, v[2:3], off offset:640
	global_load_dword v170, v[2:3], off offset:704
	s_branch .LBB0_588

; template <int MODE> __device__ __forceinline__ void gemm_epilogue(f32x4 (&acc)[2][2][4][2], const GD& g, const pg8::Unit& u, int wr, int wc, int fr, int fq, LAS unsigned char* lds, const float (&rsv)[2][4]) {
;     ...
;     if (g.f2) {
; #pragma unroll
;         for (int ai = 0; ai < 2; ++ai)
; #pragma unroll
;             for (int m = 0; m < 4; ++m) { const float rs = rsqrtf(rsv[ai][m] * (1.f / DM) + EPS);
; #pragma unroll
;                 for (int bj = 0; bj < 2; ++bj)
; #pragma unroll
;                     for (int n = 0; n < 2; ++n) acc[ai][bj][m][n] = acc[ai][bj][m][n] * rs; }
;     }
.LBB0_620:
	v_cndmask_b32_e64 v1, 0, 1, s[10:11]
	v_cmp_ne_u32_e64 s[6:7], 1, v1
	s_andn2_b64 vcc, exec, s[10:11]
	s_cbranch_vccnz .LBB0_622
	s_waitcnt vmcnt(8) lgkmcnt(0)
	v_fmamk_f32 v1, v163, 0x3a000000, v203
	v_cmp_gt_f32_e32 vcc, s80, v1
	v_mul_f32_e32 v142, 0x4b800000, v1
	s_nop 0
	v_cndmask_b32_e32 v1, v1, v142, vcc
	v_rsq_f32_e32 v1, v1
	s_nop 0
	v_mul_f32_e32 v142, 0x45800000, v1
	v_cndmask_b32_e32 v142, v1, v142, vcc
	v_fmamk_f32 v1, v164, 0x3a000000, v203
	v_pk_mul_f32 v[128:129], v[142:143], v[128:129] op_sel_hi:[0,1]
	v_pk_mul_f32 v[126:127], v[142:143], v[126:127] op_sel_hi:[0,1]
	v_pk_mul_f32 v[124:125], v[142:143], v[124:125] op_sel_hi:[0,1]
	v_pk_mul_f32 v[122:123], v[142:143], v[122:123] op_sel_hi:[0,1]
	v_pk_mul_f32 v[120:121], v[142:143], v[120:121] op_sel_hi:[0,1]
	v_pk_mul_f32 v[118:119], v[142:143], v[118:119] op_sel_hi:[0,1]
	v_pk_mul_f32 v[112:113], v[142:143], v[112:113] op_sel_hi:[0,1]
	v_pk_mul_f32 v[110:111], v[142:143], v[110:111] op_sel_hi:[0,1]
	v_cmp_gt_f32_e32 vcc, s80, v1
	v_mul_f32_e32 v142, 0x4b800000, v1
	s_nop 0
	v_cndmask_b32_e32 v1, v1, v142, vcc
	v_rsq_f32_e32 v1, v1
	s_nop 0
	v_mul_f32_e32 v142, 0x45800000, v1
	v_cndmask_b32_e32 v142, v1, v142, vcc
	v_fmamk_f32 v1, v165, 0x3a000000, v203
	v_pk_mul_f32 v[116:117], v[142:143], v[116:117] op_sel_hi:[0,1]
	v_pk_mul_f32 v[114:115], v[142:143], v[114:115] op_sel_hi:[0,1]
	v_pk_mul_f32 v[108:109], v[142:143], v[108:109] op_sel_hi:[0,1]
	v_pk_mul_f32 v[106:107], v[142:143], v[106:107] op_sel_hi:[0,1]
	v_pk_mul_f32 v[104:105], v[142:143], v[104:105] op_sel_hi:[0,1]
	v_pk_mul_f32 v[102:103], v[142:143], v[102:103] op_sel_hi:[0,1]
	v_pk_mul_f32 v[96:97], v[142:143], v[96:97] op_sel_hi:[0,1]
	v_pk_mul_f32 v[94:95], v[142:143], v[94:95] op_sel_hi:[0,1]
	v_cmp_gt_f32_e32 vcc, s80, v1
	v_mul_f32_e32 v142, 0x4b800000, v1
	s_nop 0
	v_cndmask_b32_e32 v1, v1, v142, vcc
	v_rsq_f32_e32 v1, v1
	s_nop 0
	v_mul_f32_e32 v142, 0x45800000, v1
	v_cndmask_b32_e32 v142, v1, v142, vcc
	v_fmamk_f32 v1, v166, 0x3a000000, v203
	v_pk_mul_f32 v[100:101], v[142:143], v[100:101] op_sel_hi:[0,1]
	v_pk_mul_f32 v[98:99], v[142:143], v[98:99] op_sel_hi:[0,1]
	v_pk_mul_f32 v[92:93], v[142:143], v[92:93] op_sel_hi:[0,1]
	v_pk_mul_f32 v[90:91], v[142:143], v[90:91] op_sel_hi:[0,1]
	v_pk_mul_f32 v[88:89], v[142:143], v[88:89] op_sel_hi:[0,1]
	v_pk_mul_f32 v[86:87], v[142:143], v[86:87] op_sel_hi:[0,1]
	v_pk_mul_f32 v[80:81], v[142:143], v[80:81] op_sel_hi:[0,1]
	v_pk_mul_f32 v[78:79], v[142:143], v[78:79] op_sel_hi:[0,1]
	v_cmp_gt_f32_e32 vcc, s80, v1
	v_mul_f32_e32 v142, 0x4b800000, v1
	s_nop 0
	v_cndmask_b32_e32 v1, v1, v142, vcc
	v_rsq_f32_e32 v1, v1
	s_nop 0
	v_mul_f32_e32 v142, 0x45800000, v1
	v_cndmask_b32_e32 v142, v1, v142, vcc
	v_fmamk_f32 v1, v167, 0x3a000000, v203
	v_pk_mul_f32 v[84:85], v[142:143], v[84:85] op_sel_hi:[0,1]
	v_pk_mul_f32 v[82:83], v[142:143], v[82:83] op_sel_hi:[0,1]
	v_pk_mul_f32 v[76:77], v[142:143], v[76:77] op_sel_hi:[0,1]
	v_pk_mul_f32 v[74:75], v[142:143], v[74:75] op_sel_hi:[0,1]
	v_pk_mul_f32 v[72:73], v[142:143], v[72:73] op_sel_hi:[0,1]
	v_pk_mul_f32 v[70:71], v[142:143], v[70:71] op_sel_hi:[0,1]
	v_pk_mul_f32 v[68:69], v[142:143], v[68:69] op_sel_hi:[0,1]
	v_pk_mul_f32 v[66:67], v[142:143], v[66:67] op_sel_hi:[0,1]
	v_cmp_gt_f32_e32 vcc, s80, v1
	v_mul_f32_e32 v142, 0x4b800000, v1
	s_nop 0
	v_cndmask_b32_e32 v1, v1, v142, vcc
	v_rsq_f32_e32 v1, v1
	s_nop 0
	v_mul_f32_e32 v142, 0x45800000, v1
	v_cndmask_b32_e32 v142, v1, v142, vcc
	v_fmamk_f32 v1, v168, 0x3a000000, v203
	v_pk_mul_f32 v[64:65], v[142:143], v[64:65] op_sel_hi:[0,1]
	v_pk_mul_f32 v[62:63], v[142:143], v[62:63] op_sel_hi:[0,1]
	v_pk_mul_f32 v[60:61], v[142:143], v[60:61] op_sel_hi:[0,1]
	v_pk_mul_f32 v[58:59], v[142:143], v[58:59] op_sel_hi:[0,1]
	v_pk_mul_f32 v[56:57], v[142:143], v[56:57] op_sel_hi:[0,1]
	v_pk_mul_f32 v[54:55], v[142:143], v[54:55] op_sel_hi:[0,1]
	v_pk_mul_f32 v[48:49], v[142:143], v[48:49] op_sel_hi:[0,1]
	v_pk_mul_f32 v[46:47], v[142:143], v[46:47] op_sel_hi:[0,1]
	v_cmp_gt_f32_e32 vcc, s80, v1
	v_mul_f32_e32 v142, 0x4b800000, v1
	s_nop 0
	v_cndmask_b32_e32 v1, v1, v142, vcc
	v_rsq_f32_e32 v1, v1
	s_nop 0
	v_mul_f32_e32 v142, 0x45800000, v1
	v_cndmask_b32_e32 v142, v1, v142, vcc
	v_fmamk_f32 v1, v169, 0x3a000000, v203
	v_pk_mul_f32 v[52:53], v[142:143], v[52:53] op_sel_hi:[0,1]
	v_pk_mul_f32 v[50:51], v[142:143], v[50:51] op_sel_hi:[0,1]
	v_pk_mul_f32 v[44:45], v[142:143], v[44:45] op_sel_hi:[0,1]
	v_pk_mul_f32 v[42:43], v[142:143], v[42:43] op_sel_hi:[0,1]
	v_pk_mul_f32 v[40:41], v[142:143], v[40:41] op_sel_hi:[0,1]
	v_pk_mul_f32 v[38:39], v[142:143], v[38:39] op_sel_hi:[0,1]
	v_pk_mul_f32 v[32:33], v[142:143], v[32:33] op_sel_hi:[0,1]
	v_pk_mul_f32 v[30:31], v[142:143], v[30:31] op_sel_hi:[0,1]
	v_cmp_gt_f32_e32 vcc, s80, v1
	v_mul_f32_e32 v142, 0x4b800000, v1
	s_nop 0
	v_cndmask_b32_e32 v1, v1, v142, vcc
	v_rsq_f32_e32 v1, v1
	s_nop 0
	v_mul_f32_e32 v142, 0x45800000, v1
	v_cndmask_b32_e32 v142, v1, v142, vcc
	v_fmamk_f32 v1, v170, 0x3a000000, v203
	v_pk_mul_f32 v[36:37], v[142:143], v[36:37] op_sel_hi:[0,1]
	v_pk_mul_f32 v[34:35], v[142:143], v[34:35] op_sel_hi:[0,1]
	v_pk_mul_f32 v[28:29], v[142:143], v[28:29] op_sel_hi:[0,1]
	v_pk_mul_f32 v[26:27], v[142:143], v[26:27] op_sel_hi:[0,1]
	v_pk_mul_f32 v[24:25], v[142:143], v[24:25] op_sel_hi:[0,1]
	v_pk_mul_f32 v[22:23], v[142:143], v[22:23] op_sel_hi:[0,1]
	v_pk_mul_f32 v[16:17], v[142:143], v[16:17] op_sel_hi:[0,1]
	v_pk_mul_f32 v[14:15], v[142:143], v[14:15] op_sel_hi:[0,1]
	v_cmp_gt_f32_e32 vcc, s80, v1
	v_mul_f32_e32 v142, 0x4b800000, v1
	s_nop 0
	v_cndmask_b32_e32 v1, v1, v142, vcc
	v_rsq_f32_e32 v1, v1
	s_nop 0
	v_mul_f32_e32 v142, 0x45800000, v1
	v_cndmask_b32_e32 v142, v1, v142, vcc
	v_pk_mul_f32 v[20:21], v[142:143], v[20:21] op_sel_hi:[0,1]
	v_pk_mul_f32 v[18:19], v[142:143], v[18:19] op_sel_hi:[0,1]
	v_pk_mul_f32 v[12:13], v[142:143], v[12:13] op_sel_hi:[0,1]
	v_pk_mul_f32 v[10:11], v[142:143], v[10:11] op_sel_hi:[0,1]
	v_pk_mul_f32 v[8:9], v[142:143], v[8:9] op_sel_hi:[0,1]
	v_pk_mul_f32 v[6:7], v[142:143], v[6:7] op_sel_hi:[0,1]
	v_pk_mul_f32 v[4:5], v[142:143], v[4:5] op_sel_hi:[0,1]
	v_pk_mul_f32 v[2:3], v[142:143], v[2:3] op_sel_hi:[0,1]

; __device__ __forceinline__ unsigned cvt_pk_bf16(float lo, float hi) { f32x2 v = {lo, hi}; bf16x2_t b = __builtin_convertvector(v, bf16x2_t); return __builtin_bit_cast(unsigned, b); }
; template <int MODE> __device__ __forceinline__ void gemm_epilogue(f32x4 (&acc)[2][2][4][2], const GD& g, const pg8::Unit& u, int wr, int wc, int fr, int fq, LAS unsigned char* lds, const float (&rsv)[2][4]) {
;     ...
;         for (int ai = 0; ai < 2; ++ai)
; #pragma unroll
;             for (int m = 0; m < 4; ++m) { bf16_t* rowp = O + (size_t)(row0 + ai * 128 + m * 16) * g.ldc + col0;
; #pragma unroll
;                 for (int bj = 0; bj < 2; ++bj) { const f32x4 v0 = acc[ai][bj][m][0] * sv[bj][0], v1 = acc[ai][bj][m][1] * sv[bj][1];
;                     u32x4 w; w.x = cvt_pk_bf16(v0[0], v0[1]); w.y = cvt_pk_bf16(v0[2], v0[3]); w.z = cvt_pk_bf16(v1[0], v1[1]); w.w = cvt_pk_bf16(v1[2], v1[3]);
;                     *(u32x4*)(rowp + bj * 128) = w; } }
.LBB0_630:
	v_readlane_b32 s9, v254, 51
	s_mul_i32 s2, s2, s78
	s_mul_i32 s3, s3, s9
	s_lshl_b32 s8, s38, 8
	s_add_i32 s2, s2, s3
	s_add_i32 s2, s2, s8
	v_add_u32_e32 v1, s2, v162
	v_readlane_b32 s2, v254, 42
	v_readlane_b32 s3, v254, 43
	v_pk_mul_f32 v[128:129], v[128:129], v[144:145]
	v_pk_mul_f32 v[126:127], v[126:127], v[142:143]
	v_lshl_add_u64 v[158:159], v[158:159], 1, s[2:3]
	v_mad_i64_i32 v[160:161], s[2:3], v1, s19, 0
	v_pk_mul_f32 v[176:177], v[124:125], v[148:149]
	v_pk_mul_f32 v[124:125], v[122:123], v[146:147]
	v_lshl_add_u64 v[160:161], v[160:161], 1, v[158:159]
	v_cvt_pk_bf16_f32 v122, v126, v127
	v_cvt_pk_bf16_f32 v123, v128, v129
	v_cvt_pk_bf16_f32 v124, v124, v125
	v_cvt_pk_bf16_f32 v125, v176, v177
	flat_store_dwordx4 v[160:161], v[122:125]
	v_pk_mul_f32 v[120:121], v[120:121], v[152:153]
	v_pk_mul_f32 v[118:119], v[118:119], v[150:151]
	v_pk_mul_f32 v[122:123], v[112:113], v[156:157]
	v_pk_mul_f32 v[112:113], v[110:111], v[154:155]
	v_cvt_pk_bf16_f32 v110, v118, v119
	v_cvt_pk_bf16_f32 v111, v120, v121
	v_cvt_pk_bf16_f32 v112, v112, v113
	v_cvt_pk_bf16_f32 v113, v122, v123
	flat_store_dwordx4 v[160:161], v[110:113] offset:256
	v_pk_mul_f32 v[114:115], v[114:115], v[142:143]
	v_pk_mul_f32 v[104:105], v[104:105], v[152:153]
	v_add_u32_e32 v110, 16, v1
	v_mad_i64_i32 v[110:111], s[2:3], v110, s19, 0
	v_pk_mul_f32 v[112:113], v[116:117], v[144:145]
	v_pk_mul_f32 v[116:117], v[108:109], v[148:149]
	v_pk_mul_f32 v[108:109], v[106:107], v[146:147]
	v_lshl_add_u64 v[110:111], v[110:111], 1, v[158:159]
	v_cvt_pk_bf16_f32 v106, v114, v115
	v_cvt_pk_bf16_f32 v107, v112, v113
	v_cvt_pk_bf16_f32 v108, v108, v109
	v_cvt_pk_bf16_f32 v109, v116, v117
	flat_store_dwordx4 v[110:111], v[106:109]
	v_pk_mul_f32 v[102:103], v[102:103], v[150:151]
	v_pk_mul_f32 v[98:99], v[98:99], v[142:143]
	v_pk_mul_f32 v[106:107], v[96:97], v[156:157]
	v_pk_mul_f32 v[96:97], v[94:95], v[154:155]
	v_cvt_pk_bf16_f32 v94, v102, v103
	v_cvt_pk_bf16_f32 v95, v104, v105
	v_cvt_pk_bf16_f32 v96, v96, v97
	v_cvt_pk_bf16_f32 v97, v106, v107
	flat_store_dwordx4 v[110:111], v[94:97] offset:256
	v_pk_mul_f32 v[88:89], v[88:89], v[152:153]
	v_pk_mul_f32 v[86:87], v[86:87], v[150:151]
	v_add_u32_e32 v94, 32, v1
	v_mad_i64_i32 v[94:95], s[2:3], v94, s19, 0
	v_pk_mul_f32 v[96:97], v[100:101], v[144:145]
	v_pk_mul_f32 v[100:101], v[92:93], v[148:149]
	v_pk_mul_f32 v[92:93], v[90:91], v[146:147]
	v_lshl_add_u64 v[94:95], v[94:95], 1, v[158:159]
	v_cvt_pk_bf16_f32 v90, v98, v99
	v_cvt_pk_bf16_f32 v91, v96, v97
	v_cvt_pk_bf16_f32 v92, v92, v93
	v_cvt_pk_bf16_f32 v93, v100, v101
	flat_store_dwordx4 v[94:95], v[90:93]
	v_pk_mul_f32 v[82:83], v[82:83], v[142:143]
	v_pk_mul_f32 v[72:73], v[72:73], v[152:153]
	v_pk_mul_f32 v[90:91], v[80:81], v[156:157]
	v_pk_mul_f32 v[80:81], v[78:79], v[154:155]
	v_cvt_pk_bf16_f32 v78, v86, v87
	v_cvt_pk_bf16_f32 v79, v88, v89
	v_cvt_pk_bf16_f32 v80, v80, v81
	v_cvt_pk_bf16_f32 v81, v90, v91
	flat_store_dwordx4 v[94:95], v[78:81] offset:256
	v_pk_mul_f32 v[70:71], v[70:71], v[150:151]
	v_pk_mul_f32 v[64:65], v[64:65], v[144:145]
	v_add_u32_e32 v78, 48, v1
	v_mad_i64_i32 v[78:79], s[2:3], v78, s19, 0
	v_pk_mul_f32 v[80:81], v[84:85], v[144:145]
	v_pk_mul_f32 v[84:85], v[76:77], v[148:149]
	v_pk_mul_f32 v[76:77], v[74:75], v[146:147]
	v_lshl_add_u64 v[78:79], v[78:79], 1, v[158:159]
	v_cvt_pk_bf16_f32 v74, v82, v83
	v_cvt_pk_bf16_f32 v75, v80, v81
	v_cvt_pk_bf16_f32 v76, v76, v77
	v_cvt_pk_bf16_f32 v77, v84, v85
	flat_store_dwordx4 v[78:79], v[74:77]
	v_pk_mul_f32 v[62:63], v[62:63], v[142:143]
	v_pk_mul_f32 v[56:57], v[56:57], v[152:153]
	v_pk_mul_f32 v[74:75], v[68:69], v[156:157]
	v_pk_mul_f32 v[68:69], v[66:67], v[154:155]
	v_cvt_pk_bf16_f32 v66, v70, v71
	v_cvt_pk_bf16_f32 v67, v72, v73
	v_cvt_pk_bf16_f32 v68, v68, v69
	v_cvt_pk_bf16_f32 v69, v74, v75
	flat_store_dwordx4 v[78:79], v[66:69] offset:256
	v_pk_mul_f32 v[54:55], v[54:55], v[150:151]
	v_pk_mul_f32 v[50:51], v[50:51], v[142:143]
	v_add_u32_e32 v66, 0x80, v1
	v_mad_i64_i32 v[66:67], s[2:3], v66, s19, 0
	v_pk_mul_f32 v[68:69], v[60:61], v[148:149]
	v_pk_mul_f32 v[60:61], v[58:59], v[146:147]
; __device__ __forceinline__ unsigned cvt_pk_bf16(float lo, float hi) { f32x2 v = {lo, hi}; bf16x2_t b = __builtin_convertvector(v, bf16x2_t); return __builtin_bit_cast(unsigned, b); }
; template <int MODE> __device__ __forceinline__ void gemm_epilogue(f32x4 (&acc)[2][2][4][2], const GD& g, const pg8::Unit& u, int wr, int wc, int fr, int fq, LAS unsigned char* lds, const float (&rsv)[2][4]) {
;     ...
;         for (int ai = 0; ai < 2; ++ai)
; #pragma unroll
;             for (int m = 0; m < 4; ++m) { bf16_t* rowp = O + (size_t)(row0 + ai * 128 + m * 16) * g.ldc + col0;
; #pragma unroll
;                 for (int bj = 0; bj < 2; ++bj) { const f32x4 v0 = acc[ai][bj][m][0] * sv[bj][0], v1 = acc[ai][bj][m][1] * sv[bj][1];
;                     u32x4 w; w.x = cvt_pk_bf16(v0[0], v0[1]); w.y = cvt_pk_bf16(v0[2], v0[3]); w.z = cvt_pk_bf16(v1[0], v1[1]); w.w = cvt_pk_bf16(v1[2], v1[3]);
;                     *(u32x4*)(rowp + bj * 128) = w; } }
; __device__ __forceinline__ void rsv_load(float (&rsv)[2][4], const GD& g, const pg8::Unit& u, int wr, int fr) {
;     if (g.f2) { const int rg = (u.z / g.nz2) * g.ro1 + u.pm * 256 + wr * 64 + fr;
; #pragma unroll
;         for (int ai = 0; ai < 2; ++ai)
; #pragma unroll
;             for (int m = 0; m < 4; ++m) rsv[ai][m] = g.f2[rg + ai * 128 + m * 16]; }
	v_lshl_add_u64 v[66:67], v[66:67], 1, v[158:159]
	v_cvt_pk_bf16_f32 v58, v62, v63
	v_cvt_pk_bf16_f32 v59, v64, v65
	v_cvt_pk_bf16_f32 v60, v60, v61
	v_cvt_pk_bf16_f32 v61, v68, v69
	flat_store_dwordx4 v[66:67], v[58:61]
	v_pk_mul_f32 v[40:41], v[40:41], v[152:153]
	v_pk_mul_f32 v[38:39], v[38:39], v[150:151]
	v_pk_mul_f32 v[58:59], v[48:49], v[156:157]
	v_pk_mul_f32 v[48:49], v[46:47], v[154:155]
	v_cvt_pk_bf16_f32 v46, v54, v55
	v_cvt_pk_bf16_f32 v47, v56, v57
	v_cvt_pk_bf16_f32 v48, v48, v49
	v_cvt_pk_bf16_f32 v49, v58, v59
	flat_store_dwordx4 v[66:67], v[46:49] offset:256
	v_pk_mul_f32 v[34:35], v[34:35], v[142:143]
	v_pk_mul_f32 v[24:25], v[24:25], v[152:153]
	v_add_u32_e32 v46, 0x90, v1
	v_mad_i64_i32 v[46:47], s[2:3], v46, s19, 0
	v_pk_mul_f32 v[48:49], v[52:53], v[144:145]
	v_pk_mul_f32 v[52:53], v[44:45], v[148:149]
	v_pk_mul_f32 v[44:45], v[42:43], v[146:147]
	v_lshl_add_u64 v[46:47], v[46:47], 1, v[158:159]
	v_cvt_pk_bf16_f32 v42, v50, v51
	v_cvt_pk_bf16_f32 v43, v48, v49
	v_cvt_pk_bf16_f32 v44, v44, v45
	v_cvt_pk_bf16_f32 v45, v52, v53
	flat_store_dwordx4 v[46:47], v[42:45]
	v_pk_mul_f32 v[22:23], v[22:23], v[150:151]
	v_pk_mul_f32 v[18:19], v[18:19], v[142:143]
	v_pk_mul_f32 v[42:43], v[32:33], v[156:157]
	v_pk_mul_f32 v[32:33], v[30:31], v[154:155]
	v_cvt_pk_bf16_f32 v30, v38, v39
	v_cvt_pk_bf16_f32 v31, v40, v41
	v_cvt_pk_bf16_f32 v32, v32, v33
	v_cvt_pk_bf16_f32 v33, v42, v43
	flat_store_dwordx4 v[46:47], v[30:33] offset:256
	v_pk_mul_f32 v[8:9], v[8:9], v[152:153]
	v_pk_mul_f32 v[6:7], v[6:7], v[150:151]
	v_add_u32_e32 v30, 0xa0, v1
	v_mad_i64_i32 v[30:31], s[2:3], v30, s19, 0
	v_pk_mul_f32 v[32:33], v[36:37], v[144:145]
	v_pk_mul_f32 v[36:37], v[28:29], v[148:149]
	v_pk_mul_f32 v[28:29], v[26:27], v[146:147]
	v_lshl_add_u64 v[30:31], v[30:31], 1, v[158:159]
	v_cvt_pk_bf16_f32 v26, v34, v35
	v_cvt_pk_bf16_f32 v27, v32, v33
	v_cvt_pk_bf16_f32 v28, v28, v29
	v_cvt_pk_bf16_f32 v29, v36, v37
	flat_store_dwordx4 v[30:31], v[26:29]
	v_add_u32_e32 v1, 0xb0, v1
	s_andn2_b64 vcc, exec, s[68:69]
	v_pk_mul_f32 v[26:27], v[16:17], v[156:157]
	v_pk_mul_f32 v[16:17], v[14:15], v[154:155]
	v_cvt_pk_bf16_f32 v14, v22, v23
	v_cvt_pk_bf16_f32 v15, v24, v25
	v_cvt_pk_bf16_f32 v16, v16, v17
	v_cvt_pk_bf16_f32 v17, v26, v27
	flat_store_dwordx4 v[30:31], v[14:17] offset:256
	s_nop 1
	v_mad_i64_i32 v[14:15], s[2:3], v1, s19, 0
	v_pk_mul_f32 v[16:17], v[20:21], v[144:145]
	v_pk_mul_f32 v[20:21], v[12:13], v[148:149]
	v_pk_mul_f32 v[12:13], v[10:11], v[146:147]
	v_lshl_add_u64 v[14:15], v[14:15], 1, v[158:159]
	v_cvt_pk_bf16_f32 v10, v18, v19
	v_cvt_pk_bf16_f32 v11, v16, v17
	v_cvt_pk_bf16_f32 v12, v12, v13
	v_cvt_pk_bf16_f32 v13, v20, v21
	flat_store_dwordx4 v[14:15], v[10:13]
	s_mov_b64 s[2:3], -1
	s_nop 0
	v_pk_mul_f32 v[10:11], v[4:5], v[156:157]
	v_pk_mul_f32 v[4:5], v[2:3], v[154:155]
	v_cvt_pk_bf16_f32 v2, v6, v7
	v_cvt_pk_bf16_f32 v3, v8, v9
	v_cvt_pk_bf16_f32 v4, v4, v5
	v_cvt_pk_bf16_f32 v5, v10, v11
	flat_store_dwordx4 v[14:15], v[2:5] offset:256
	s_cbranch_vccnz .LBB0_592
	s_and_b64 vcc, exec, s[6:7]
	s_cbranch_vccnz .LBB0_633
	s_abs_i32 s3, s12
	s_mul_hi_u32 s6, s3, s35
	s_mul_i32 s7, s6, s94
	s_ashr_i32 s2, s12, 31
	s_sub_i32 s3, s3, s7
	s_xor_b32 s2, s2, s51
	s_add_i32 s7, s6, 1
	s_sub_i32 s8, s3, s94
	s_cmp_ge_u32 s3, s94
	s_cselect_b32 s6, s7, s6
	s_cselect_b32 s3, s8, s3
	s_add_i32 s7, s6, 1
	s_cmp_ge_u32 s3, s94
	s_cselect_b32 s3, s7, s6
	s_xor_b32 s3, s3, s2
	s_sub_i32 s2, s3, s2
	s_mul_i32 s2, s2, s78
	s_lshl_b32 s3, s13, 8
	s_add_i32 s2, s2, s3
	v_add_u32_e32 v2, s2, v162
	v_readlane_b32 s2, v254, 52
	v_ashrrev_i32_e32 v3, 31, v2
	v_readlane_b32 s3, v254, 53
	s_nop 1
	v_lshl_add_u64 v[2:3], v[2:3], 2, s[2:3]
	s_waitcnt vmcnt(0) lgkmcnt(0)
	global_load_dword v163, v[2:3], off
	global_load_dword v164, v[2:3], off offset:64
	global_load_dword v165, v[2:3], off offset:128
	global_load_dword v166, v[2:3], off offset:192
	global_load_dword v167, v[2:3], off offset:512
	global_load_dword v168, v[2:3], off offset:576
	global_load_dword v169, v[2:3], off offset:640
	global_load_dword v170, v[2:3], off offset:704
